# speedup vs baseline: 1.0180x; 1.0012x over previous
; #define LAS __attribute__((address_space(3)))
; #define MFMA16(a, b, c) __builtin_amdgcn_mfma_f32_16x16x32_bf16((a), (b), (c), 0, 0, 0)
; #define RET_ISSUE(s_, it_) do { const bf16_t* bp_; int pt_; RET_SRC(s_, it_, bp_, pt_); const int tv_ = otid(); const char* sb_ = (const char*)bp_ + (size_t)(((tv_ >> 5) * pt_ + (tv_ & 31) * 8) * 2); const size_t step_ = (size_t)pt_ * 32; \
;         _Pragma("unroll") for (int i_ = 0; i_ < 8; ++i_) stg[i_] = *(const u32x4*)(sb_ + i_ * step_); } while (0)
; __device__ void ret_out_phase(LAS unsigned char* lds, const bf16_t* PROJ, const bf16_t* ST, bf16_t* MIX, const float* lgf, const float* lgb, const float* ogain) {
;     ...
;     for (; item < 768; item += gridDim.x) {
;         const RetItem ri = ret_decode(item);
;         const int h = ri.h, half = ri.half, qt = ri.qt;
;         const float lf = lgf[h], lb = lgb[h];
;         const size_t qtok = (size_t)qt * 128 + 16 * wave + fr;
;         bf16x8 qf[8];
; #pragma unroll
;         for (int ks = 0; ks < 8; ++ks) qf[ks] = *(const bf16x8*)(PROJ + pj(qtok, 3072 + h * 256 + 32 * ks + 8 * g));
;         f32x4 o[16];
; #pragma unroll
;         for (int cc = 0; cc < 16; ++cc) o[cc] = (f32x4){0.f, 0.f, 0.f, 0.f};
;         f32x4 st[8];
; #pragma unroll
;         for (int s = 0; s < 8; ++s) {
;             LAS unsigned char* buf = lds + (s & 1) * BUFB;
; #pragma unroll
;             for (int i = 0; i < 8; ++i) *(LAS u32x4*)(buf + ((tid >> 5) + 16 * i) * RP + (tid & 31) * 16) = stg[i];
;             __syncthreads();
;             if (s < 7) { RET_ISSUE(s + 1, ri); }
;             else if (item + (int)gridDim.x < 768) { const RetItem rn = ret_decode(item + gridDim.x); RET_ISSUE(0, rn); }
;             if (s < 4) {
; #pragma unroll
;                 for (int ccl = 0; ccl < 8; ++ccl)
; #pragma unroll
;                     for (int ks = 0; ks < 8; ++ks) { const bf16x8 bfrag = *(const LAS bf16x8*)(buf + (16 * ccl + fr) * RP + (32 * ks + 8 * g) * 2); o[(s & 1) * 8 + ccl] = MFMA16(qf[ks], bfrag, o[(s & 1) * 8 + ccl]); }
.LBB0_35:
	s_ashr_i32 s1, s14, 1
	s_and_b32 s0, s14, 4
	s_and_b32 s1, s1, -8
	s_or_b32 s4, s1, s0
	s_bfe_u32 s5, s14, 0x10003
	s_and_b32 s12, s14, 3
	s_ashr_i32 s0, s4, 1
	s_or_b32 s0, s0, s5
	s_lshl_b32 s1, s12, 2
	v_mov_b32_e32 v0, s1
	s_ashr_i32 s1, s0, 31
	s_lshl_b64 s[0:1], s[0:1], 7
	s_add_u32 s2, s0, s6
	s_mul_i32 s13, s12, 0x6000
	global_load_dword v184, v0, s[38:39]
	global_load_dword v185, v0, s[40:41]
	s_addc_u32 s3, s1, s7
	v_or_b32_e32 v0, s13, v165
	v_lshl_add_u64 v[34:35], s[2:3], 0, v[0:1]
	v_lshlrev_b64 v[34:35], 9, v[34:35]
	v_lshl_add_u64 v[34:35], s[78:79], 0, v[34:35]
	v_mov_b32_e32 v167, v1
	v_lshl_add_u64 v[34:35], v[34:35], 0, v[166:167]
	v_lshl_add_u64 v[36:37], v[34:35], 0, s[16:17]
	v_add_co_u32_e32 v34, vcc, s33, v34
	s_ashr_i32 s0, s4, 2
	s_nop 0
	v_addc_co_u32_e32 v35, vcc, 0, v35, vcc
	global_load_dwordx4 v[62:65], v[34:35], off
	global_load_dwordx4 v[58:61], v[36:37], off offset:64
	global_load_dwordx4 v[54:57], v[36:37], off offset:128
	global_load_dwordx4 v[50:53], v[36:37], off offset:192
	global_load_dwordx4 v[46:49], v[36:37], off offset:256
	global_load_dwordx4 v[42:45], v[36:37], off offset:320
	global_load_dwordx4 v[38:41], v[36:37], off offset:384
	s_nop 0
	global_load_dwordx4 v[34:37], v[36:37], off offset:448
	s_lshl_b32 s5, s5, 7
	v_or_b32_e32 v0, s6, v165
	v_or_b32_e32 v66, s6, v190
	s_or_b32 s4, s4, s12
	s_ashr_i32 s1, s0, 31
	v_add_u32_e32 v0, s5, v0
	v_add_u32_e32 v167, s5, v66
	s_waitcnt vmcnt(17)
	ds_write_b128 v210, v[2:5]
	s_waitcnt vmcnt(16)
	ds_write_b128 v210, v[6:9] offset:8448
	s_waitcnt vmcnt(15)
	ds_write_b128 v210, v[10:13] offset:16896
	s_waitcnt vmcnt(14)
	ds_write_b128 v210, v[14:17] offset:25344
	s_waitcnt vmcnt(13)
	ds_write_b128 v210, v[18:21] offset:33792
	s_waitcnt vmcnt(12)
	ds_write_b128 v210, v[22:25] offset:42240
	s_waitcnt vmcnt(11)
	ds_write_b128 v210, v[26:29] offset:50688
	s_waitcnt vmcnt(10)
	ds_write_b128 v210, v[30:33] offset:59136
	s_ashr_i32 s5, s4, 31
	v_mov_b32_e32 v2, v226
	s_lshl_b64 s[0:1], s[0:1], 8
	s_waitcnt lgkmcnt(0)
	s_barrier
	s_lshl_b64 s[16:17], s[4:5], 17
	s_add_u32 s16, s84, s16
	v_lshlrev_b32_e32 v2, 4, v2
	s_addc_u32 s17, s85, s17
	v_ashrrev_i32_e32 v3, 31, v2
	v_lshl_add_u64 v[2:3], s[16:17], 0, v[2:3]
	s_mov_b32 s16, 0x10000
	v_add_co_u32_e32 v4, vcc, s16, v2
	s_mov_b32 s17, 0x12000
	s_nop 0
	v_addc_co_u32_e32 v5, vcc, 0, v3, vcc
	global_load_dwordx4 v[26:29], v[4:5], off
	v_add_co_u32_e32 v4, vcc, s17, v2
	s_mov_b32 s18, 0x14000
	s_nop 0
	v_addc_co_u32_e32 v5, vcc, 0, v3, vcc
	global_load_dwordx4 v[30:33], v[4:5], off
	v_add_co_u32_e32 v4, vcc, s18, v2
	s_mov_b32 s20, 0x16000
	s_nop 0
	v_addc_co_u32_e32 v5, vcc, 0, v3, vcc
	global_load_dwordx4 v[70:73], v[4:5], off
	v_add_co_u32_e32 v4, vcc, s20, v2
	s_mov_b32 s21, 0x18000
	s_nop 0
	v_addc_co_u32_e32 v5, vcc, 0, v3, vcc
	global_load_dwordx4 v[74:77], v[4:5], off
	v_add_co_u32_e32 v4, vcc, s21, v2
	s_mov_b32 s22, 0x1a000
	s_nop 0
	v_addc_co_u32_e32 v5, vcc, 0, v3, vcc
	global_load_dwordx4 v[78:81], v[4:5], off
	v_add_co_u32_e32 v4, vcc, s22, v2
	s_mov_b32 s23, 0x1c000
	s_nop 0
	v_addc_co_u32_e32 v5, vcc, 0, v3, vcc
	global_load_dwordx4 v[82:85], v[4:5], off
	v_add_co_u32_e32 v4, vcc, s23, v2
	s_mov_b32 s24, 0x1e000
	s_nop 0
	v_addc_co_u32_e32 v5, vcc, 0, v3, vcc
	v_add_co_u32_e32 v2, vcc, s24, v2
	global_load_dwordx4 v[86:89], v[4:5], off
	s_nop 0
	v_addc_co_u32_e32 v3, vcc, 0, v3, vcc
	global_load_dwordx4 v[90:93], v[2:3], off
	ds_read_b128 v[2:5], v191
	ds_read_b128 v[6:9], v191 offset:64
	s_waitcnt vmcnt(15) lgkmcnt(1)
	v_mfma_f32_16x16x32_bf16 v[2:5], v[62:65], v[2:5], 0
	ds_read_b128 v[10:13], v191 offset:8512
	ds_read_b128 v[14:17], v191 offset:16960
	ds_read_b128 v[18:21], v191 offset:25408
	s_waitcnt vmcnt(14) lgkmcnt(3)
	v_mfma_f32_16x16x32_bf16 v[2:5], v[58:61], v[6:9], v[2:5]
	ds_read_b128 v[6:9], v191 offset:128
	s_addk_i32 s4, 0x180
	s_ashr_i32 s5, s4, 31
	s_waitcnt vmcnt(13) lgkmcnt(0)
	v_mfma_f32_16x16x32_bf16 v[2:5], v[54:57], v[6:9], v[2:5]
	ds_read_b128 v[6:9], v191 offset:192
	s_lshl_b64 s[4:5], s[4:5], 17
	s_add_u32 s4, s84, s4
	s_waitcnt vmcnt(12) lgkmcnt(0)
	v_mfma_f32_16x16x32_bf16 v[2:5], v[50:53], v[6:9], v[2:5]
	ds_read_b128 v[6:9], v191 offset:256
	s_addc_u32 s5, s85, s5
	s_movk_i32 s15, 0x2000
	s_waitcnt vmcnt(11) lgkmcnt(0)
	v_mfma_f32_16x16x32_bf16 v[2:5], v[46:49], v[6:9], v[2:5]
	ds_read_b128 v[6:9], v191 offset:320
	v_sub_u32_e32 v173, v0, v190
	ds_read_b128 v[22:25], v191 offset:33856
	s_waitcnt vmcnt(10) lgkmcnt(1)
	v_mfma_f32_16x16x32_bf16 v[2:5], v[42:45], v[6:9], v[2:5]
	ds_read_b128 v[6:9], v191 offset:384
	ds_read_b128 v[66:69], v191 offset:42304
	ds_read_b128 v[94:97], v191 offset:50752
	s_waitcnt vmcnt(9) lgkmcnt(2)
	v_mfma_f32_16x16x32_bf16 v[2:5], v[38:41], v[6:9], v[2:5]
	ds_read_b128 v[6:9], v191 offset:448
	ds_read_b128 v[98:101], v191 offset:59200
	s_waitcnt vmcnt(8) lgkmcnt(1)
	v_mfma_f32_16x16x32_bf16 v[2:5], v[34:37], v[6:9], v[2:5]
	ds_read_b128 v[6:9], v191 offset:8448
	s_waitcnt lgkmcnt(0)
	v_mfma_f32_16x16x32_bf16 v[6:9], v[62:65], v[6:9], 0
	v_mfma_f32_16x16x32_bf16 v[6:9], v[58:61], v[10:13], v[6:9]
	ds_read_b128 v[10:13], v191 offset:8576
	ds_read_b128 v[102:105], v191 offset:8640
	ds_read_b128 v[106:109], v191 offset:8704
	ds_read_b128 v[110:113], v191 offset:8768
	s_waitcnt lgkmcnt(3)
	v_mfma_f32_16x16x32_bf16 v[6:9], v[54:57], v[10:13], v[6:9]
	ds_read_b128 v[10:13], v191 offset:8832
	s_waitcnt lgkmcnt(3)
	v_mfma_f32_16x16x32_bf16 v[6:9], v[50:53], v[102:105], v[6:9]
	ds_read_b128 v[102:105], v191 offset:8896
	s_waitcnt lgkmcnt(3)
	v_mfma_f32_16x16x32_bf16 v[6:9], v[46:49], v[106:109], v[6:9]
	s_waitcnt lgkmcnt(2)
; #define LAS __attribute__((address_space(3)))
; #define MFMA16(a, b, c) __builtin_amdgcn_mfma_f32_16x16x32_bf16((a), (b), (c), 0, 0, 0)
; __device__ void ret_out_phase(LAS unsigned char* lds, const bf16_t* PROJ, const bf16_t* ST, bf16_t* MIX, const float* lgf, const float* lgb, const float* ogain) {
;     ...
;             for (int i = 0; i < 8; ++i) *(LAS u32x4*)(buf + ((tid >> 5) + 16 * i) * RP + (tid & 31) * 16) = stg[i];
;             __syncthreads();
;     ...
;             if (s < 4) {
; #pragma unroll
;                 for (int ccl = 0; ccl < 8; ++ccl)
; #pragma unroll
;                     for (int ks = 0; ks < 8; ++ks) { const bf16x8 bfrag = *(const LAS bf16x8*)(buf + (16 * ccl + fr) * RP + (32 * ks + 8 * g) * 2); o[(s & 1) * 8 + ccl] = MFMA16(qf[ks], bfrag, o[(s & 1) * 8 + ccl]); }
	v_mfma_f32_16x16x32_bf16 v[6:9], v[42:45], v[110:113], v[6:9]
	s_waitcnt lgkmcnt(1)
	v_mfma_f32_16x16x32_bf16 v[6:9], v[38:41], v[10:13], v[6:9]
	s_waitcnt lgkmcnt(0)
	v_mfma_f32_16x16x32_bf16 v[6:9], v[34:37], v[102:105], v[6:9]
	ds_read_b128 v[10:13], v191 offset:16896
	s_waitcnt lgkmcnt(0)
	v_mfma_f32_16x16x32_bf16 v[10:13], v[62:65], v[10:13], 0
	v_mfma_f32_16x16x32_bf16 v[10:13], v[58:61], v[14:17], v[10:13]
	ds_read_b128 v[14:17], v191 offset:17024
	ds_read_b128 v[102:105], v191 offset:17088
	ds_read_b128 v[106:109], v191 offset:17152
	ds_read_b128 v[110:113], v191 offset:17216
	s_waitcnt lgkmcnt(3)
	v_mfma_f32_16x16x32_bf16 v[10:13], v[54:57], v[14:17], v[10:13]
	ds_read_b128 v[14:17], v191 offset:17280
	s_waitcnt lgkmcnt(3)
	v_mfma_f32_16x16x32_bf16 v[10:13], v[50:53], v[102:105], v[10:13]
	ds_read_b128 v[102:105], v191 offset:17344
	s_waitcnt lgkmcnt(3)
	v_mfma_f32_16x16x32_bf16 v[10:13], v[46:49], v[106:109], v[10:13]
	s_waitcnt lgkmcnt(2)
	v_mfma_f32_16x16x32_bf16 v[10:13], v[42:45], v[110:113], v[10:13]
	s_waitcnt lgkmcnt(1)
	v_mfma_f32_16x16x32_bf16 v[10:13], v[38:41], v[14:17], v[10:13]
	s_waitcnt lgkmcnt(0)
	v_mfma_f32_16x16x32_bf16 v[10:13], v[34:37], v[102:105], v[10:13]
	ds_read_b128 v[14:17], v191 offset:25344
	s_waitcnt lgkmcnt(0)
	v_mfma_f32_16x16x32_bf16 v[14:17], v[62:65], v[14:17], 0
	v_mfma_f32_16x16x32_bf16 v[14:17], v[58:61], v[18:21], v[14:17]
	ds_read_b128 v[18:21], v191 offset:25472
	ds_read_b128 v[102:105], v191 offset:25536
	ds_read_b128 v[106:109], v191 offset:25600
	ds_read_b128 v[110:113], v191 offset:25664
	s_waitcnt lgkmcnt(3)
	v_mfma_f32_16x16x32_bf16 v[14:17], v[54:57], v[18:21], v[14:17]
	ds_read_b128 v[18:21], v191 offset:25728
	s_waitcnt lgkmcnt(3)
	v_mfma_f32_16x16x32_bf16 v[14:17], v[50:53], v[102:105], v[14:17]
	ds_read_b128 v[102:105], v191 offset:25792
	s_waitcnt lgkmcnt(3)
	v_mfma_f32_16x16x32_bf16 v[14:17], v[46:49], v[106:109], v[14:17]
	s_waitcnt lgkmcnt(2)
	v_mfma_f32_16x16x32_bf16 v[14:17], v[42:45], v[110:113], v[14:17]
	s_waitcnt lgkmcnt(1)
	v_mfma_f32_16x16x32_bf16 v[14:17], v[38:41], v[18:21], v[14:17]
	s_waitcnt lgkmcnt(0)
	v_mfma_f32_16x16x32_bf16 v[14:17], v[34:37], v[102:105], v[14:17]
	ds_read_b128 v[18:21], v191 offset:33792
	s_waitcnt lgkmcnt(0)
	v_mfma_f32_16x16x32_bf16 v[18:21], v[62:65], v[18:21], 0
	v_mfma_f32_16x16x32_bf16 v[18:21], v[58:61], v[22:25], v[18:21]
	ds_read_b128 v[22:25], v191 offset:33920
	ds_read_b128 v[102:105], v191 offset:33984
	ds_read_b128 v[106:109], v191 offset:34048
	ds_read_b128 v[110:113], v191 offset:34112
	s_waitcnt lgkmcnt(3)
	v_mfma_f32_16x16x32_bf16 v[18:21], v[54:57], v[22:25], v[18:21]
	ds_read_b128 v[22:25], v191 offset:34176
	s_waitcnt lgkmcnt(3)
	v_mfma_f32_16x16x32_bf16 v[18:21], v[50:53], v[102:105], v[18:21]
	ds_read_b128 v[102:105], v191 offset:34240
	s_waitcnt lgkmcnt(3)
	v_mfma_f32_16x16x32_bf16 v[18:21], v[46:49], v[106:109], v[18:21]
	s_waitcnt lgkmcnt(2)
	v_mfma_f32_16x16x32_bf16 v[18:21], v[42:45], v[110:113], v[18:21]
	s_waitcnt lgkmcnt(1)
	v_mfma_f32_16x16x32_bf16 v[18:21], v[38:41], v[22:25], v[18:21]
	s_waitcnt lgkmcnt(0)
	v_mfma_f32_16x16x32_bf16 v[18:21], v[34:37], v[102:105], v[18:21]
	ds_read_b128 v[22:25], v191 offset:42240
	s_waitcnt lgkmcnt(0)
	v_mfma_f32_16x16x32_bf16 v[22:25], v[62:65], v[22:25], 0
	v_mfma_f32_16x16x32_bf16 v[22:25], v[58:61], v[66:69], v[22:25]
	ds_read_b128 v[66:69], v191 offset:42368
	ds_read_b128 v[102:105], v191 offset:42432
	ds_read_b128 v[106:109], v191 offset:42496
	ds_read_b128 v[110:113], v191 offset:42560
	s_waitcnt lgkmcnt(3)
	v_mfma_f32_16x16x32_bf16 v[22:25], v[54:57], v[66:69], v[22:25]
	ds_read_b128 v[66:69], v191 offset:42624
	s_waitcnt lgkmcnt(3)
	v_mfma_f32_16x16x32_bf16 v[22:25], v[50:53], v[102:105], v[22:25]
	ds_read_b128 v[102:105], v191 offset:42688
	s_waitcnt lgkmcnt(3)
	v_mfma_f32_16x16x32_bf16 v[22:25], v[46:49], v[106:109], v[22:25]
	s_waitcnt lgkmcnt(2)
	v_mfma_f32_16x16x32_bf16 v[22:25], v[42:45], v[110:113], v[22:25]
	s_waitcnt lgkmcnt(1)
	v_mfma_f32_16x16x32_bf16 v[22:25], v[38:41], v[66:69], v[22:25]
	s_waitcnt lgkmcnt(0)
	v_mfma_f32_16x16x32_bf16 v[22:25], v[34:37], v[102:105], v[22:25]
	ds_read_b128 v[66:69], v191 offset:50688
	s_waitcnt lgkmcnt(0)
	v_mfma_f32_16x16x32_bf16 v[66:69], v[62:65], v[66:69], 0
	v_mfma_f32_16x16x32_bf16 v[66:69], v[58:61], v[94:97], v[66:69]
	ds_read_b128 v[94:97], v191 offset:50816
	ds_read_b128 v[102:105], v191 offset:50880
	ds_read_b128 v[106:109], v191 offset:50944
	ds_read_b128 v[110:113], v191 offset:51008
	s_waitcnt lgkmcnt(3)
	v_mfma_f32_16x16x32_bf16 v[66:69], v[54:57], v[94:97], v[66:69]
	ds_read_b128 v[94:97], v191 offset:51072
	s_waitcnt lgkmcnt(3)
	v_mfma_f32_16x16x32_bf16 v[66:69], v[50:53], v[102:105], v[66:69]
	ds_read_b128 v[102:105], v191 offset:51136
	s_waitcnt lgkmcnt(3)
	v_mfma_f32_16x16x32_bf16 v[66:69], v[46:49], v[106:109], v[66:69]
	s_waitcnt lgkmcnt(2)
	v_mfma_f32_16x16x32_bf16 v[66:69], v[42:45], v[110:113], v[66:69]
	s_waitcnt lgkmcnt(1)
	v_mfma_f32_16x16x32_bf16 v[66:69], v[38:41], v[94:97], v[66:69]
	s_waitcnt lgkmcnt(0)
	v_mfma_f32_16x16x32_bf16 v[66:69], v[34:37], v[102:105], v[66:69]
	ds_read_b128 v[94:97], v191 offset:59136
	s_waitcnt lgkmcnt(0)
	v_mfma_f32_16x16x32_bf16 v[94:97], v[62:65], v[94:97], 0
	v_mfma_f32_16x16x32_bf16 v[94:97], v[58:61], v[98:101], v[94:97]
	ds_read_b128 v[98:101], v191 offset:59264
	ds_read_b128 v[102:105], v191 offset:59328
	ds_read_b128 v[106:109], v191 offset:59392
	ds_read_b128 v[110:113], v191 offset:59456
	s_waitcnt lgkmcnt(3)
	v_mfma_f32_16x16x32_bf16 v[94:97], v[54:57], v[98:101], v[94:97]
	ds_read_b128 v[98:101], v191 offset:59520
	s_waitcnt lgkmcnt(3)
	v_mfma_f32_16x16x32_bf16 v[94:97], v[50:53], v[102:105], v[94:97]
	s_waitcnt lgkmcnt(2)
	v_mfma_f32_16x16x32_bf16 v[94:97], v[46:49], v[106:109], v[94:97]
	s_waitcnt lgkmcnt(1)
	v_mfma_f32_16x16x32_bf16 v[94:97], v[42:45], v[110:113], v[94:97]
	s_waitcnt lgkmcnt(0)
	v_mfma_f32_16x16x32_bf16 v[94:97], v[38:41], v[98:101], v[94:97]
	ds_read_b128 v[98:101], v191 offset:59584
	s_waitcnt vmcnt(7)
	ds_write_b128 v211, v[26:29]
	s_waitcnt vmcnt(6)
	ds_write_b128 v211, v[30:33] offset:8448
	s_waitcnt vmcnt(5)
	ds_write_b128 v211, v[70:73] offset:16896
	s_waitcnt vmcnt(4)
	ds_write_b128 v211, v[74:77] offset:25344
	s_waitcnt vmcnt(3)
	ds_write_b128 v211, v[78:81] offset:33792
	s_waitcnt vmcnt(2)
	ds_write_b128 v211, v[82:85] offset:42240
	s_waitcnt vmcnt(1)
	ds_write_b128 v211, v[86:89] offset:50688
	s_waitcnt vmcnt(0)
	ds_write_b128 v211, v[90:93] offset:59136
	v_mov_b32_e32 v26, v226
	s_waitcnt lgkmcnt(0)
	s_barrier
; #define LAS __attribute__((address_space(3)))
; #define MFMA16(a, b, c) __builtin_amdgcn_mfma_f32_16x16x32_bf16((a), (b), (c), 0, 0, 0)
; #define RET_ISSUE(s_, it_) do { const bf16_t* bp_; int pt_; RET_SRC(s_, it_, bp_, pt_); const int tv_ = otid(); const char* sb_ = (const char*)bp_ + (size_t)(((tv_ >> 5) * pt_ + (tv_ & 31) * 8) * 2); const size_t step_ = (size_t)pt_ * 32; \
;         _Pragma("unroll") for (int i_ = 0; i_ < 8; ++i_) stg[i_] = *(const u32x4*)(sb_ + i_ * step_); } while (0)
; __device__ void ret_out_phase(LAS unsigned char* lds, const bf16_t* PROJ, const bf16_t* ST, bf16_t* MIX, const float* lgf, const float* lgb, const float* ogain) {
;     ...
;             if (s < 7) { RET_ISSUE(s + 1, ri); }
;             else if (item + (int)gridDim.x < 768) { const RetItem rn = ret_decode(item + gridDim.x); RET_ISSUE(0, rn); }
;             if (s < 4) {
; #pragma unroll
;                 for (int ccl = 0; ccl < 8; ++ccl)
; #pragma unroll
;                     for (int ks = 0; ks < 8; ++ks) { const bf16x8 bfrag = *(const LAS bf16x8*)(buf + (16 * ccl + fr) * RP + (32 * ks + 8 * g) * 2); o[(s & 1) * 8 + ccl] = MFMA16(qf[ks], bfrag, o[(s & 1) * 8 + ccl]); }
	v_mfma_f32_16x16x32_bf16 v[94:97], v[34:37], v[98:101], v[94:97]
	v_lshlrev_b32_e32 v26, 4, v26
	v_ashrrev_i32_e32 v27, 31, v26
	v_lshl_add_u64 v[70:71], s[4:5], 0, v[26:27]
	v_add_co_u32_e32 v30, vcc, s15, v70
	s_movk_i32 s15, 0x4000
	s_nop 0
	v_addc_co_u32_e32 v31, vcc, 0, v71, vcc
	v_add_co_u32_e32 v72, vcc, s15, v70
	s_movk_i32 s15, 0x6000
	s_nop 0
	v_addc_co_u32_e32 v73, vcc, 0, v71, vcc
	global_load_dwordx4 v[98:101], v[72:73], off
	v_add_co_u32_e32 v72, vcc, s15, v70
	s_mov_b32 s15, 0x8000
	s_nop 0
	v_addc_co_u32_e32 v73, vcc, 0, v71, vcc
	global_load_dwordx4 v[102:105], v[72:73], off
	v_add_co_u32_e32 v72, vcc, s15, v70
	s_mov_b32 s15, 0xa000
	s_nop 0
	v_addc_co_u32_e32 v73, vcc, 0, v71, vcc
	global_load_dwordx4 v[106:109], v[72:73], off
	v_add_co_u32_e32 v72, vcc, s15, v70
	s_mov_b32 s15, 0xc000
	s_nop 0
	v_addc_co_u32_e32 v73, vcc, 0, v71, vcc
	global_load_dwordx4 v[110:113], v[72:73], off
	v_add_co_u32_e32 v72, vcc, s15, v70
	s_mov_b32 s15, 0xe000
	s_nop 0
	v_addc_co_u32_e32 v73, vcc, 0, v71, vcc
	global_load_dwordx4 v[26:29], v[70:71], off
	global_load_dwordx4 v[114:117], v[72:73], off
	ds_read_b128 v[74:77], v192 offset:64
	global_load_dwordx4 v[30:33], v[30:31], off
	v_add_co_u32_e32 v70, vcc, s15, v70
	ds_read_b128 v[78:81], v192 offset:8512
	s_nop 0
	v_addc_co_u32_e32 v71, vcc, 0, v71, vcc
	global_load_dwordx4 v[118:121], v[70:71], off
	ds_read_b128 v[70:73], v192
	s_waitcnt lgkmcnt(0)
	v_mfma_f32_16x16x32_bf16 v[70:73], v[62:65], v[70:73], 0
	ds_read_b128 v[82:85], v192 offset:16960
	ds_read_b128 v[86:89], v192 offset:25408
	s_add_i32 s15, s13, 0x18000
	v_mfma_f32_16x16x32_bf16 v[70:73], v[58:61], v[74:77], v[70:73]
	ds_read_b128 v[74:77], v192 offset:128
	ds_read_b128 v[90:93], v192 offset:33856
	ds_read_b128 v[122:125], v192 offset:42304
	s_waitcnt lgkmcnt(2)
	v_mfma_f32_16x16x32_bf16 v[70:73], v[54:57], v[74:77], v[70:73]
	ds_read_b128 v[74:77], v192 offset:192
	ds_read_b128 v[126:129], v192 offset:50752
	s_waitcnt lgkmcnt(1)
	v_mfma_f32_16x16x32_bf16 v[70:73], v[50:53], v[74:77], v[70:73]
	ds_read_b128 v[74:77], v192 offset:256
	ds_read_b128 v[130:133], v192 offset:320
	ds_read_b128 v[134:137], v192 offset:384
	ds_read_b128 v[138:141], v192 offset:448
	s_waitcnt lgkmcnt(3)
	v_mfma_f32_16x16x32_bf16 v[70:73], v[46:49], v[74:77], v[70:73]
	s_waitcnt lgkmcnt(2)
	v_mfma_f32_16x16x32_bf16 v[70:73], v[42:45], v[130:133], v[70:73]
	s_waitcnt lgkmcnt(1)
	v_mfma_f32_16x16x32_bf16 v[70:73], v[38:41], v[134:137], v[70:73]
	s_waitcnt lgkmcnt(0)
	v_mfma_f32_16x16x32_bf16 v[70:73], v[34:37], v[138:141], v[70:73]
	ds_read_b128 v[74:77], v192 offset:8448
	s_waitcnt lgkmcnt(0)
	v_mfma_f32_16x16x32_bf16 v[74:77], v[62:65], v[74:77], 0
	v_mfma_f32_16x16x32_bf16 v[74:77], v[58:61], v[78:81], v[74:77]
	ds_read_b128 v[78:81], v192 offset:8576
	ds_read_b128 v[130:133], v192 offset:8640
	ds_read_b128 v[134:137], v192 offset:8704
	ds_read_b128 v[138:141], v192 offset:8768
	s_waitcnt lgkmcnt(3)
	v_mfma_f32_16x16x32_bf16 v[74:77], v[54:57], v[78:81], v[74:77]
	ds_read_b128 v[78:81], v192 offset:8832
	s_waitcnt lgkmcnt(3)
	v_mfma_f32_16x16x32_bf16 v[74:77], v[50:53], v[130:133], v[74:77]
	ds_read_b128 v[130:133], v192 offset:8896
	s_waitcnt lgkmcnt(3)
	v_mfma_f32_16x16x32_bf16 v[74:77], v[46:49], v[134:137], v[74:77]
	s_waitcnt lgkmcnt(2)
	v_mfma_f32_16x16x32_bf16 v[74:77], v[42:45], v[138:141], v[74:77]
	s_waitcnt lgkmcnt(1)
	v_mfma_f32_16x16x32_bf16 v[74:77], v[38:41], v[78:81], v[74:77]
	s_waitcnt lgkmcnt(0)
	v_mfma_f32_16x16x32_bf16 v[74:77], v[34:37], v[130:133], v[74:77]
	ds_read_b128 v[78:81], v192 offset:16896
	s_waitcnt lgkmcnt(0)
	v_mfma_f32_16x16x32_bf16 v[78:81], v[62:65], v[78:81], 0
	v_mfma_f32_16x16x32_bf16 v[78:81], v[58:61], v[82:85], v[78:81]
	ds_read_b128 v[82:85], v192 offset:17024
	ds_read_b128 v[130:133], v192 offset:17088
	ds_read_b128 v[134:137], v192 offset:17152
	ds_read_b128 v[138:141], v192 offset:17216
	s_waitcnt lgkmcnt(3)
	v_mfma_f32_16x16x32_bf16 v[78:81], v[54:57], v[82:85], v[78:81]
	ds_read_b128 v[82:85], v192 offset:17280
	s_waitcnt lgkmcnt(3)
	v_mfma_f32_16x16x32_bf16 v[78:81], v[50:53], v[130:133], v[78:81]
	ds_read_b128 v[130:133], v192 offset:17344
	s_waitcnt lgkmcnt(3)
	v_mfma_f32_16x16x32_bf16 v[78:81], v[46:49], v[134:137], v[78:81]
	s_waitcnt lgkmcnt(2)
	v_mfma_f32_16x16x32_bf16 v[78:81], v[42:45], v[138:141], v[78:81]
	s_waitcnt lgkmcnt(1)
	v_mfma_f32_16x16x32_bf16 v[78:81], v[38:41], v[82:85], v[78:81]
	s_waitcnt lgkmcnt(0)
	v_mfma_f32_16x16x32_bf16 v[78:81], v[34:37], v[130:133], v[78:81]
	ds_read_b128 v[82:85], v192 offset:25344
	s_waitcnt lgkmcnt(0)
	v_mfma_f32_16x16x32_bf16 v[82:85], v[62:65], v[82:85], 0
	v_mfma_f32_16x16x32_bf16 v[82:85], v[58:61], v[86:89], v[82:85]
	ds_read_b128 v[86:89], v192 offset:25472
	ds_read_b128 v[130:133], v192 offset:25536
	ds_read_b128 v[134:137], v192 offset:25600
	ds_read_b128 v[138:141], v192 offset:25664
	s_waitcnt lgkmcnt(3)
	v_mfma_f32_16x16x32_bf16 v[82:85], v[54:57], v[86:89], v[82:85]
	ds_read_b128 v[86:89], v192 offset:25728
	s_waitcnt lgkmcnt(3)
	v_mfma_f32_16x16x32_bf16 v[82:85], v[50:53], v[130:133], v[82:85]
	ds_read_b128 v[130:133], v192 offset:25792
	s_waitcnt lgkmcnt(3)
	v_mfma_f32_16x16x32_bf16 v[82:85], v[46:49], v[134:137], v[82:85]
	s_waitcnt lgkmcnt(2)
	v_mfma_f32_16x16x32_bf16 v[82:85], v[42:45], v[138:141], v[82:85]
	s_waitcnt lgkmcnt(1)
	v_mfma_f32_16x16x32_bf16 v[82:85], v[38:41], v[86:89], v[82:85]
	s_waitcnt lgkmcnt(0)
	v_mfma_f32_16x16x32_bf16 v[82:85], v[34:37], v[130:133], v[82:85]
	ds_read_b128 v[86:89], v192 offset:33792
	s_waitcnt lgkmcnt(0)
; #define LAS __attribute__((address_space(3)))
; #define MFMA16(a, b, c) __builtin_amdgcn_mfma_f32_16x16x32_bf16((a), (b), (c), 0, 0, 0)
; __device__ void ret_out_phase(LAS unsigned char* lds, const bf16_t* PROJ, const bf16_t* ST, bf16_t* MIX, const float* lgf, const float* lgb, const float* ogain) {
;     ...
;             for (int i = 0; i < 8; ++i) *(LAS u32x4*)(buf + ((tid >> 5) + 16 * i) * RP + (tid & 31) * 16) = stg[i];
;             __syncthreads();
;     ...
;             if (s < 4) {
; #pragma unroll
;                 for (int ccl = 0; ccl < 8; ++ccl)
; #pragma unroll
;                     for (int ks = 0; ks < 8; ++ks) { const bf16x8 bfrag = *(const LAS bf16x8*)(buf + (16 * ccl + fr) * RP + (32 * ks + 8 * g) * 2); o[(s & 1) * 8 + ccl] = MFMA16(qf[ks], bfrag, o[(s & 1) * 8 + ccl]); }
	v_mfma_f32_16x16x32_bf16 v[86:89], v[62:65], v[86:89], 0
	v_mfma_f32_16x16x32_bf16 v[86:89], v[58:61], v[90:93], v[86:89]
	ds_read_b128 v[90:93], v192 offset:33920
	ds_read_b128 v[130:133], v192 offset:33984
	ds_read_b128 v[134:137], v192 offset:34048
	ds_read_b128 v[138:141], v192 offset:34112
	s_waitcnt lgkmcnt(3)
	v_mfma_f32_16x16x32_bf16 v[86:89], v[54:57], v[90:93], v[86:89]
	ds_read_b128 v[90:93], v192 offset:34176
	s_waitcnt lgkmcnt(3)
	v_mfma_f32_16x16x32_bf16 v[86:89], v[50:53], v[130:133], v[86:89]
	ds_read_b128 v[130:133], v192 offset:34240
	s_waitcnt lgkmcnt(3)
	v_mfma_f32_16x16x32_bf16 v[86:89], v[46:49], v[134:137], v[86:89]
	s_waitcnt lgkmcnt(2)
	v_mfma_f32_16x16x32_bf16 v[86:89], v[42:45], v[138:141], v[86:89]
	s_waitcnt lgkmcnt(1)
	v_mfma_f32_16x16x32_bf16 v[86:89], v[38:41], v[90:93], v[86:89]
	s_waitcnt lgkmcnt(0)
	v_mfma_f32_16x16x32_bf16 v[86:89], v[34:37], v[130:133], v[86:89]
	ds_read_b128 v[90:93], v192 offset:42240
	s_waitcnt lgkmcnt(0)
	v_mfma_f32_16x16x32_bf16 v[90:93], v[62:65], v[90:93], 0
	v_mfma_f32_16x16x32_bf16 v[90:93], v[58:61], v[122:125], v[90:93]
	ds_read_b128 v[122:125], v192 offset:42368
	ds_read_b128 v[130:133], v192 offset:42432
	ds_read_b128 v[134:137], v192 offset:42496
	ds_read_b128 v[138:141], v192 offset:42560
	s_waitcnt lgkmcnt(3)
	v_mfma_f32_16x16x32_bf16 v[90:93], v[54:57], v[122:125], v[90:93]
	ds_read_b128 v[122:125], v192 offset:42624
	s_waitcnt lgkmcnt(3)
	v_mfma_f32_16x16x32_bf16 v[90:93], v[50:53], v[130:133], v[90:93]
	ds_read_b128 v[130:133], v192 offset:42688
	s_waitcnt lgkmcnt(3)
	v_mfma_f32_16x16x32_bf16 v[90:93], v[46:49], v[134:137], v[90:93]
	s_waitcnt lgkmcnt(2)
	v_mfma_f32_16x16x32_bf16 v[90:93], v[42:45], v[138:141], v[90:93]
	s_waitcnt lgkmcnt(1)
	v_mfma_f32_16x16x32_bf16 v[90:93], v[38:41], v[122:125], v[90:93]
	s_waitcnt lgkmcnt(0)
	v_mfma_f32_16x16x32_bf16 v[90:93], v[34:37], v[130:133], v[90:93]
	ds_read_b128 v[122:125], v192 offset:50688
	s_waitcnt lgkmcnt(0)
	v_mfma_f32_16x16x32_bf16 v[122:125], v[62:65], v[122:125], 0
	v_mfma_f32_16x16x32_bf16 v[122:125], v[58:61], v[126:129], v[122:125]
	ds_read_b128 v[126:129], v192 offset:50816
	ds_read_b128 v[134:137], v192 offset:50880
	ds_read_b128 v[138:141], v192 offset:50944
	ds_read_b128 v[142:145], v192 offset:51008
	s_waitcnt lgkmcnt(3)
	v_mfma_f32_16x16x32_bf16 v[122:125], v[54:57], v[126:129], v[122:125]
	ds_read_b128 v[126:129], v192 offset:51072
	s_waitcnt lgkmcnt(3)
	v_mfma_f32_16x16x32_bf16 v[122:125], v[50:53], v[134:137], v[122:125]
	ds_read_b128 v[134:137], v192 offset:51136
	s_waitcnt lgkmcnt(3)
	v_mfma_f32_16x16x32_bf16 v[122:125], v[46:49], v[138:141], v[122:125]
	s_waitcnt lgkmcnt(2)
	v_mfma_f32_16x16x32_bf16 v[122:125], v[42:45], v[142:145], v[122:125]
	s_waitcnt lgkmcnt(1)
	v_mfma_f32_16x16x32_bf16 v[122:125], v[38:41], v[126:129], v[122:125]
	s_waitcnt lgkmcnt(0)
	v_mfma_f32_16x16x32_bf16 v[130:133], v[34:37], v[134:137], v[122:125]
	ds_read_b128 v[126:129], v192 offset:59200
	s_nop 3
	ds_read_b128 v[122:125], v192 offset:59136
	s_waitcnt lgkmcnt(0)
	v_mfma_f32_16x16x32_bf16 v[122:125], v[62:65], v[122:125], 0
	v_mfma_f32_16x16x32_bf16 v[122:125], v[58:61], v[126:129], v[122:125]
	ds_read_b128 v[126:129], v192 offset:59264
	ds_read_b128 v[134:137], v192 offset:59328
	ds_read_b128 v[138:141], v192 offset:59392
	ds_read_b128 v[142:145], v192 offset:59456
	s_waitcnt lgkmcnt(3)
	v_mfma_f32_16x16x32_bf16 v[122:125], v[54:57], v[126:129], v[122:125]
	ds_read_b128 v[126:129], v192 offset:59520
	s_waitcnt lgkmcnt(3)
	v_mfma_f32_16x16x32_bf16 v[122:125], v[50:53], v[134:137], v[122:125]
	s_waitcnt lgkmcnt(2)
	v_mfma_f32_16x16x32_bf16 v[122:125], v[46:49], v[138:141], v[122:125]
	s_waitcnt lgkmcnt(1)
	v_mfma_f32_16x16x32_bf16 v[122:125], v[42:45], v[142:145], v[122:125]
	s_waitcnt lgkmcnt(0)
	v_mfma_f32_16x16x32_bf16 v[122:125], v[38:41], v[126:129], v[122:125]
	ds_read_b128 v[126:129], v192 offset:59584
	s_waitcnt vmcnt(3)
	ds_write_b128 v210, v[26:29]
	s_waitcnt vmcnt(1)
	ds_write_b128 v210, v[30:33] offset:8448
	ds_write_b128 v210, v[98:101] offset:16896
	ds_write_b128 v210, v[102:105] offset:25344
	ds_write_b128 v210, v[106:109] offset:33792
	ds_write_b128 v210, v[110:113] offset:42240
	ds_write_b128 v210, v[114:117] offset:50688
	s_waitcnt vmcnt(0)
	ds_write_b128 v210, v[118:121] offset:59136
	s_waitcnt lgkmcnt(0)
	v_mfma_f32_16x16x32_bf16 v[134:137], v[34:37], v[126:129], v[122:125]
	s_barrier
; #define LAS __attribute__((address_space(3)))
; #define MFMA16(a, b, c) __builtin_amdgcn_mfma_f32_16x16x32_bf16((a), (b), (c), 0, 0, 0)
; #define RET_ISSUE(s_, it_) do { const bf16_t* bp_; int pt_; RET_SRC(s_, it_, bp_, pt_); const int tv_ = otid(); const char* sb_ = (const char*)bp_ + (size_t)(((tv_ >> 5) * pt_ + (tv_ & 31) * 8) * 2); const size_t step_ = (size_t)pt_ * 32; \
;         _Pragma("unroll") for (int i_ = 0; i_ < 8; ++i_) stg[i_] = *(const u32x4*)(sb_ + i_ * step_); } while (0)
; __device__ void ret_out_phase(LAS unsigned char* lds, const bf16_t* PROJ, const bf16_t* ST, bf16_t* MIX, const float* lgf, const float* lgb, const float* ogain) {
;     ...
;             if (s < 7) { RET_ISSUE(s + 1, ri); }
;             else if (item + (int)gridDim.x < 768) { const RetItem rn = ret_decode(item + gridDim.x); RET_ISSUE(0, rn); }
;             if (s < 4) {
; #pragma unroll
;                 for (int ccl = 0; ccl < 8; ++ccl)
; #pragma unroll
;                     for (int ks = 0; ks < 8; ++ks) { const bf16x8 bfrag = *(const LAS bf16x8*)(buf + (16 * ccl + fr) * RP + (32 * ks + 8 * g) * 2); o[(s & 1) * 8 + ccl] = MFMA16(qf[ks], bfrag, o[(s & 1) * 8 + ccl]); }
;                 if (s & 1) {
; #pragma unroll
;                     for (int j = 0; j < 4; ++j) { const int il = half * 128 + 16 * wave + 4 * g + j;
;                         const float sc = s == 1 ? __expf(lf * (float)(il + 1) - lb * (float)(256 - il)) : __expf(lb * (float)(256 - il));
; #pragma unroll
;                         for (int cc = 0; cc < 16; ++cc) o[cc][j] *= sc; }
;                 }
	s_nop 1
	v_sub_u32_e32 v124, 0x100, v167
	v_or_b32_e32 v122, 1, v167
	v_cvt_f32_i32_e32 v124, v124
	v_cvt_f32_i32_e32 v123, v122
	v_sub_u32_e32 v122, 0x100, v122
	v_cvt_f32_i32_e32 v122, v122
	v_mul_f32_e32 v169, v185, v124
	v_fma_f32 v123, v184, v123, -v169
	v_mul_f32_e32 v123, 0x3fb8aa3b, v123
	v_exp_f32_e32 v142, v123
	v_or_b32_e32 v123, 2, v167
	v_cvt_f32_i32_e32 v124, v123
	v_mul_f32_e32 v122, v185, v122
	v_sub_u32_e32 v123, 0x100, v123
	v_cvt_f32_i32_e32 v123, v123
	v_fma_f32 v122, v184, v124, -v122
	v_mul_f32_e32 v122, 0x3fb8aa3b, v122
	v_exp_f32_e32 v143, v122
	v_or_b32_e32 v122, 3, v167
	v_cvt_f32_i32_e32 v124, v122
	v_mul_f32_e32 v171, v185, v123
	v_pk_mul_f32 v[138:139], v[142:143], v[2:3]
	v_pk_mul_f32 v[2:3], v[142:143], v[6:7]
	v_fma_f32 v123, v184, v124, -v171
	v_mul_f32_e32 v123, 0x3fb8aa3b, v123
	v_exp_f32_e32 v144, v123
	v_sub_u32_e32 v123, 0x100, v122
	v_add_u32_e32 v122, 4, v167
	v_cvt_f32_i32_e32 v122, v122
	v_cvt_f32_i32_e32 v123, v123
	v_pk_mul_f32 v[6:7], v[142:143], v[10:11]
	v_pk_mul_f32 v[10:11], v[142:143], v[14:15]
	v_mov_b32_e32 v14, v226
	v_pk_mul_f32 v[186:187], v[184:185], v[122:123]
	s_nop 0
	v_sub_f32_e32 v122, v186, v187
	v_mul_f32_e32 v122, 0x3fb8aa3b, v122
	v_exp_f32_e32 v145, v122
	v_pk_mul_f32 v[126:127], v[142:143], v[66:67]
	v_lshlrev_b32_e32 v14, 4, v14
	v_ashrrev_i32_e32 v15, 31, v14
	v_lshl_add_u64 v[14:15], s[4:5], 0, v[14:15]
	v_pk_mul_f32 v[140:141], v[144:145], v[4:5]
	v_pk_mul_f32 v[4:5], v[144:145], v[8:9]
	v_pk_mul_f32 v[8:9], v[144:145], v[12:13]
	v_pk_mul_f32 v[12:13], v[144:145], v[16:17]
	v_add_co_u32_e32 v16, vcc, s16, v14
	v_pk_mul_f32 v[128:129], v[144:145], v[68:69]
	s_nop 0
	v_addc_co_u32_e32 v17, vcc, 0, v15, vcc
	global_load_dwordx4 v[98:101], v[16:17], off
	v_add_co_u32_e32 v16, vcc, s17, v14
	v_pk_mul_f32 v[124:125], v[144:145], v[96:97]
	s_nop 0
	v_addc_co_u32_e32 v17, vcc, 0, v15, vcc
	global_load_dwordx4 v[102:105], v[16:17], off
	v_add_co_u32_e32 v16, vcc, s18, v14
	v_pk_mul_f32 v[122:123], v[142:143], v[94:95]
	s_nop 0
	v_addc_co_u32_e32 v17, vcc, 0, v15, vcc
	global_load_dwordx4 v[106:109], v[16:17], off
	v_add_co_u32_e32 v16, vcc, s20, v14
	v_pk_mul_f32 v[68:69], v[144:145], v[72:73]
	s_nop 0
	v_addc_co_u32_e32 v17, vcc, 0, v15, vcc
	global_load_dwordx4 v[110:113], v[16:17], off
	v_add_co_u32_e32 v16, vcc, s21, v14
	v_pk_mul_f32 v[66:67], v[142:143], v[70:71]
	s_nop 0
	v_addc_co_u32_e32 v17, vcc, 0, v15, vcc
	global_load_dwordx4 v[114:117], v[16:17], off
	v_add_co_u32_e32 v16, vcc, s22, v14
	v_pk_mul_f32 v[72:73], v[144:145], v[76:77]
	s_nop 0
	v_addc_co_u32_e32 v17, vcc, 0, v15, vcc
	global_load_dwordx4 v[118:121], v[16:17], off
	v_add_co_u32_e32 v16, vcc, s23, v14
	v_pk_mul_f32 v[70:71], v[142:143], v[74:75]
	s_nop 0
	v_addc_co_u32_e32 v17, vcc, 0, v15, vcc
	v_add_co_u32_e32 v14, vcc, s24, v14
	v_pk_mul_f32 v[76:77], v[144:145], v[80:81]
	s_nop 0
	v_addc_co_u32_e32 v15, vcc, 0, v15, vcc
	v_pk_mul_f32 v[74:75], v[142:143], v[78:79]
	v_pk_mul_f32 v[80:81], v[144:145], v[84:85]
	v_pk_mul_f32 v[78:79], v[142:143], v[82:83]
	v_pk_mul_f32 v[84:85], v[144:145], v[88:89]
	v_pk_mul_f32 v[82:83], v[142:143], v[86:87]
	v_pk_mul_f32 v[88:89], v[144:145], v[92:93]
	v_pk_mul_f32 v[86:87], v[142:143], v[90:91]
	v_pk_mul_f32 v[92:93], v[144:145], v[132:133]
	v_pk_mul_f32 v[90:91], v[142:143], v[130:131]
	v_pk_mul_f32 v[96:97], v[144:145], v[136:137]
	v_pk_mul_f32 v[94:95], v[142:143], v[134:135]
	global_load_dwordx4 v[130:133], v[16:17], off
	global_load_dwordx4 v[134:137], v[14:15], off
	ds_read_b128 v[14:17], v191
	ds_read_b128 v[26:29], v191 offset:64
	s_waitcnt lgkmcnt(1)
	v_mfma_f32_16x16x32_bf16 v[14:17], v[62:65], v[14:17], v[138:141]
	v_mul_f32_e64 v20, v144, v20
	v_mul_f32_e64 v21, v145, v21
	v_pk_mul_f32 v[18:19], v[142:143], v[18:19]
	ds_read_b128 v[30:33], v191 offset:50752
	s_waitcnt lgkmcnt(1)
	v_mfma_f32_16x16x32_bf16 v[14:17], v[58:61], v[26:29], v[14:17]
	ds_read_b128 v[26:29], v191 offset:128
	v_pk_mul_f32 v[24:25], v[144:145], v[24:25]
	v_pk_mul_f32 v[22:23], v[142:143], v[22:23]
	s_waitcnt lgkmcnt(0)
	v_mfma_f32_16x16x32_bf16 v[14:17], v[54:57], v[26:29], v[14:17]
	ds_read_b128 v[26:29], v191 offset:192
	s_add_u32 s4, s0, s15
	s_addc_u32 s5, s1, 0
	s_waitcnt lgkmcnt(0)
	v_mfma_f32_16x16x32_bf16 v[14:17], v[50:53], v[26:29], v[14:17]
	ds_read_b128 v[26:29], v191 offset:256
	s_lshl_b64 s[4:5], s[4:5], 9
	s_add_u32 s4, s78, s4
	s_waitcnt lgkmcnt(0)
	v_mfma_f32_16x16x32_bf16 v[14:17], v[46:49], v[26:29], v[14:17]
	ds_read_b128 v[26:29], v191 offset:320
	s_addc_u32 s5, s79, s5
	s_mov_b32 s17, 0x9002000
	s_waitcnt lgkmcnt(0)
	v_mfma_f32_16x16x32_bf16 v[14:17], v[42:45], v[26:29], v[14:17]
	ds_read_b128 v[26:29], v191 offset:384
	s_mov_b32 s18, 0x9004000
	s_mov_b32 s20, 0x9006000
	s_waitcnt lgkmcnt(0)
	v_mfma_f32_16x16x32_bf16 v[14:17], v[38:41], v[26:29], v[14:17]
	ds_read_b128 v[26:29], v191 offset:448
	s_mov_b32 s21, 0x9008000
	s_mov_b32 s22, 0x900a000
	s_waitcnt lgkmcnt(0)
	v_mfma_f32_16x16x32_bf16 v[14:17], v[34:37], v[26:29], v[14:17]
	ds_read_b128 v[26:29], v191 offset:8448
	s_mov_b32 s23, 0x900c000
	s_mov_b32 s24, 0x900e000
	s_waitcnt lgkmcnt(0)
	v_mfma_f32_16x16x32_bf16 v[2:5], v[62:65], v[26:29], v[2:5]
	ds_read_b128 v[26:29], v191 offset:8512
	s_add_i32 s16, s13, 0x30000
	s_waitcnt lgkmcnt(0)
	v_mfma_f32_16x16x32_bf16 v[2:5], v[58:61], v[26:29], v[2:5]
	ds_read_b128 v[26:29], v191 offset:8576
	ds_read_b128 v[138:141], v191 offset:8640
	ds_read_b128 v[142:145], v191 offset:8704
	ds_read_b128 v[146:149], v191 offset:8768
	s_waitcnt lgkmcnt(3)
	v_mfma_f32_16x16x32_bf16 v[2:5], v[54:57], v[26:29], v[2:5]
	ds_read_b128 v[26:29], v191 offset:8832
	s_waitcnt lgkmcnt(3)
; #define LAS __attribute__((address_space(3)))
; #define MFMA16(a, b, c) __builtin_amdgcn_mfma_f32_16x16x32_bf16((a), (b), (c), 0, 0, 0)
; __device__ void ret_out_phase(LAS unsigned char* lds, const bf16_t* PROJ, const bf16_t* ST, bf16_t* MIX, const float* lgf, const float* lgb, const float* ogain) {
;     ...
;                 for (int ccl = 0; ccl < 8; ++ccl)
; #pragma unroll
;                     for (int ks = 0; ks < 8; ++ks) { const bf16x8 bfrag = *(const LAS bf16x8*)(buf + (16 * ccl + fr) * RP + (32 * ks + 8 * g) * 2); o[(s & 1) * 8 + ccl] = MFMA16(qf[ks], bfrag, o[(s & 1) * 8 + ccl]); }
	v_mfma_f32_16x16x32_bf16 v[2:5], v[50:53], v[138:141], v[2:5]
	ds_read_b128 v[138:141], v191 offset:8896
	s_waitcnt lgkmcnt(3)
	v_mfma_f32_16x16x32_bf16 v[2:5], v[46:49], v[142:145], v[2:5]
	ds_read_b128 v[142:145], v191 offset:16896
	s_waitcnt lgkmcnt(3)
	v_mfma_f32_16x16x32_bf16 v[2:5], v[42:45], v[146:149], v[2:5]
	ds_read_b128 v[146:149], v191 offset:16960
	s_waitcnt lgkmcnt(3)
	v_mfma_f32_16x16x32_bf16 v[2:5], v[38:41], v[26:29], v[2:5]
	ds_read_b128 v[26:29], v191 offset:17024
	s_waitcnt lgkmcnt(3)
	v_mfma_f32_16x16x32_bf16 v[2:5], v[34:37], v[138:141], v[2:5]
	ds_read_b128 v[138:141], v191 offset:17088
	s_waitcnt lgkmcnt(3)
	v_mfma_f32_16x16x32_bf16 v[6:9], v[62:65], v[142:145], v[6:9]
	ds_read_b128 v[142:145], v191 offset:17152
	s_waitcnt lgkmcnt(3)
	v_mfma_f32_16x16x32_bf16 v[6:9], v[58:61], v[146:149], v[6:9]
	ds_read_b128 v[146:149], v191 offset:17216
	s_waitcnt lgkmcnt(3)
	v_mfma_f32_16x16x32_bf16 v[6:9], v[54:57], v[26:29], v[6:9]
	ds_read_b128 v[26:29], v191 offset:17280
	s_waitcnt lgkmcnt(3)
	v_mfma_f32_16x16x32_bf16 v[6:9], v[50:53], v[138:141], v[6:9]
	ds_read_b128 v[138:141], v191 offset:17344
	s_waitcnt lgkmcnt(3)
	v_mfma_f32_16x16x32_bf16 v[6:9], v[46:49], v[142:145], v[6:9]
	ds_read_b128 v[142:145], v191 offset:25344
	s_waitcnt lgkmcnt(3)
	v_mfma_f32_16x16x32_bf16 v[6:9], v[42:45], v[146:149], v[6:9]
	ds_read_b128 v[146:149], v191 offset:25408
	s_waitcnt lgkmcnt(3)
	v_mfma_f32_16x16x32_bf16 v[6:9], v[38:41], v[26:29], v[6:9]
	ds_read_b128 v[26:29], v191 offset:25472
	s_waitcnt lgkmcnt(3)
	v_mfma_f32_16x16x32_bf16 v[6:9], v[34:37], v[138:141], v[6:9]
	ds_read_b128 v[138:141], v191 offset:25536
	s_waitcnt lgkmcnt(3)
	v_mfma_f32_16x16x32_bf16 v[10:13], v[62:65], v[142:145], v[10:13]
	ds_read_b128 v[142:145], v191 offset:25600
	s_waitcnt lgkmcnt(3)
	v_mfma_f32_16x16x32_bf16 v[10:13], v[58:61], v[146:149], v[10:13]
	ds_read_b128 v[146:149], v191 offset:25664
	s_waitcnt lgkmcnt(3)
	v_mfma_f32_16x16x32_bf16 v[10:13], v[54:57], v[26:29], v[10:13]
	ds_read_b128 v[26:29], v191 offset:25728
	s_waitcnt lgkmcnt(3)
	v_mfma_f32_16x16x32_bf16 v[10:13], v[50:53], v[138:141], v[10:13]
	ds_read_b128 v[138:141], v191 offset:25792
	s_waitcnt lgkmcnt(3)
	v_mfma_f32_16x16x32_bf16 v[10:13], v[46:49], v[142:145], v[10:13]
	ds_read_b128 v[142:145], v191 offset:33792
	s_waitcnt lgkmcnt(3)
	v_mfma_f32_16x16x32_bf16 v[10:13], v[42:45], v[146:149], v[10:13]
	ds_read_b128 v[146:149], v191 offset:33856
	s_waitcnt lgkmcnt(3)
	v_mfma_f32_16x16x32_bf16 v[10:13], v[38:41], v[26:29], v[10:13]
	ds_read_b128 v[26:29], v191 offset:33920
	s_waitcnt lgkmcnt(3)
	v_mfma_f32_16x16x32_bf16 v[10:13], v[34:37], v[138:141], v[10:13]
	ds_read_b128 v[138:141], v191 offset:33984
	s_waitcnt lgkmcnt(3)
	v_mfma_f32_16x16x32_bf16 v[18:21], v[62:65], v[142:145], v[18:21]
	ds_read_b128 v[142:145], v191 offset:34048
	s_waitcnt lgkmcnt(3)
	v_mfma_f32_16x16x32_bf16 v[18:21], v[58:61], v[146:149], v[18:21]
	ds_read_b128 v[146:149], v191 offset:34112
	s_waitcnt lgkmcnt(3)
	v_mfma_f32_16x16x32_bf16 v[18:21], v[54:57], v[26:29], v[18:21]
	ds_read_b128 v[26:29], v191 offset:34176
	s_waitcnt lgkmcnt(3)
	v_mfma_f32_16x16x32_bf16 v[18:21], v[50:53], v[138:141], v[18:21]
	ds_read_b128 v[138:141], v191 offset:34240
	s_waitcnt lgkmcnt(3)
	v_mfma_f32_16x16x32_bf16 v[18:21], v[46:49], v[142:145], v[18:21]
	ds_read_b128 v[142:145], v191 offset:42240
	s_waitcnt lgkmcnt(3)
	v_mfma_f32_16x16x32_bf16 v[18:21], v[42:45], v[146:149], v[18:21]
	ds_read_b128 v[146:149], v191 offset:42304
	s_waitcnt lgkmcnt(3)
	v_mfma_f32_16x16x32_bf16 v[18:21], v[38:41], v[26:29], v[18:21]
	ds_read_b128 v[26:29], v191 offset:42368
	s_waitcnt lgkmcnt(3)
	v_mfma_f32_16x16x32_bf16 v[18:21], v[34:37], v[138:141], v[18:21]
	ds_read_b128 v[138:141], v191 offset:42432
	s_waitcnt lgkmcnt(3)
	v_mfma_f32_16x16x32_bf16 v[22:25], v[62:65], v[142:145], v[22:25]
	ds_read_b128 v[142:145], v191 offset:42496
	s_waitcnt lgkmcnt(3)
	v_mfma_f32_16x16x32_bf16 v[22:25], v[58:61], v[146:149], v[22:25]
	ds_read_b128 v[146:149], v191 offset:42560
	s_waitcnt lgkmcnt(3)
	v_mfma_f32_16x16x32_bf16 v[22:25], v[54:57], v[26:29], v[22:25]
	ds_read_b128 v[26:29], v191 offset:42624
	s_waitcnt lgkmcnt(3)
	v_mfma_f32_16x16x32_bf16 v[22:25], v[50:53], v[138:141], v[22:25]
	ds_read_b128 v[138:141], v191 offset:42688
	s_waitcnt lgkmcnt(3)
	v_mfma_f32_16x16x32_bf16 v[22:25], v[46:49], v[142:145], v[22:25]
	s_waitcnt lgkmcnt(2)
	v_mfma_f32_16x16x32_bf16 v[22:25], v[42:45], v[146:149], v[22:25]
	s_waitcnt lgkmcnt(1)
	v_mfma_f32_16x16x32_bf16 v[22:25], v[38:41], v[26:29], v[22:25]
	s_waitcnt lgkmcnt(0)
	v_mfma_f32_16x16x32_bf16 v[22:25], v[34:37], v[138:141], v[22:25]
	ds_read_b128 v[26:29], v191 offset:50688
	s_waitcnt lgkmcnt(0)
	v_mfma_f32_16x16x32_bf16 v[26:29], v[62:65], v[26:29], v[126:129]
	v_mfma_f32_16x16x32_bf16 v[26:29], v[58:61], v[30:33], v[26:29]
	ds_read_b128 v[30:33], v191 offset:50816
	ds_read_b128 v[126:129], v191 offset:50880
	ds_read_b128 v[138:141], v191 offset:50944
	ds_read_b128 v[142:145], v191 offset:51008
	s_waitcnt lgkmcnt(3)
	v_mfma_f32_16x16x32_bf16 v[26:29], v[54:57], v[30:33], v[26:29]
	ds_read_b128 v[30:33], v191 offset:51072
	s_waitcnt lgkmcnt(3)
	v_mfma_f32_16x16x32_bf16 v[26:29], v[50:53], v[126:129], v[26:29]
	ds_read_b128 v[126:129], v191 offset:51136
	s_waitcnt lgkmcnt(3)
	v_mfma_f32_16x16x32_bf16 v[26:29], v[46:49], v[138:141], v[26:29]
	s_waitcnt lgkmcnt(2)
	v_mfma_f32_16x16x32_bf16 v[26:29], v[42:45], v[142:145], v[26:29]
	s_waitcnt lgkmcnt(1)
	v_mfma_f32_16x16x32_bf16 v[26:29], v[38:41], v[30:33], v[26:29]
	s_waitcnt lgkmcnt(0)
	v_mfma_f32_16x16x32_bf16 v[26:29], v[34:37], v[126:129], v[26:29]
	ds_read_b128 v[30:33], v191 offset:59136
	s_waitcnt lgkmcnt(0)
; #define LAS __attribute__((address_space(3)))
; #define MFMA16(a, b, c) __builtin_amdgcn_mfma_f32_16x16x32_bf16((a), (b), (c), 0, 0, 0)
; #define RET_ISSUE(s_, it_) do { const bf16_t* bp_; int pt_; RET_SRC(s_, it_, bp_, pt_); const int tv_ = otid(); const char* sb_ = (const char*)bp_ + (size_t)(((tv_ >> 5) * pt_ + (tv_ & 31) * 8) * 2); const size_t step_ = (size_t)pt_ * 32; \
;         _Pragma("unroll") for (int i_ = 0; i_ < 8; ++i_) stg[i_] = *(const u32x4*)(sb_ + i_ * step_); } while (0)
; __device__ void ret_out_phase(LAS unsigned char* lds, const bf16_t* PROJ, const bf16_t* ST, bf16_t* MIX, const float* lgf, const float* lgb, const float* ogain) {
;     ...
;             for (int i = 0; i < 8; ++i) *(LAS u32x4*)(buf + ((tid >> 5) + 16 * i) * RP + (tid & 31) * 16) = stg[i];
;             __syncthreads();
;             if (s < 7) { RET_ISSUE(s + 1, ri); }
;     ...
;                 for (int ccl = 0; ccl < 8; ++ccl)
; #pragma unroll
;                     for (int ks = 0; ks < 8; ++ks) { const bf16x8 bfrag = *(const LAS bf16x8*)(buf + (16 * ccl + fr) * RP + (32 * ks + 8 * g) * 2); o[(s & 1) * 8 + ccl] = MFMA16(qf[ks], bfrag, o[(s & 1) * 8 + ccl]); }
	v_mfma_f32_16x16x32_bf16 v[30:33], v[62:65], v[30:33], v[122:125]
	s_nop 2
	ds_read_b128 v[122:125], v191 offset:59200
	ds_read_b128 v[126:129], v191 offset:59264
	ds_read_b128 v[138:141], v191 offset:59328
	ds_read_b128 v[142:145], v191 offset:59392
	s_waitcnt lgkmcnt(3)
	v_mfma_f32_16x16x32_bf16 v[30:33], v[58:61], v[122:125], v[30:33]
	ds_read_b128 v[122:125], v191 offset:59456
	s_waitcnt lgkmcnt(3)
	v_mfma_f32_16x16x32_bf16 v[30:33], v[54:57], v[126:129], v[30:33]
	ds_read_b128 v[126:129], v191 offset:59520
	s_waitcnt lgkmcnt(3)
	v_mfma_f32_16x16x32_bf16 v[30:33], v[50:53], v[138:141], v[30:33]
	s_waitcnt lgkmcnt(2)
	v_mfma_f32_16x16x32_bf16 v[30:33], v[46:49], v[142:145], v[30:33]
	s_waitcnt lgkmcnt(1)
	v_mfma_f32_16x16x32_bf16 v[30:33], v[42:45], v[122:125], v[30:33]
	s_waitcnt lgkmcnt(0)
	v_mfma_f32_16x16x32_bf16 v[30:33], v[38:41], v[126:129], v[30:33]
	ds_read_b128 v[122:125], v191 offset:59584
	s_waitcnt vmcnt(7)
	ds_write_b128 v211, v[98:101]
	s_waitcnt vmcnt(6)
	ds_write_b128 v211, v[102:105] offset:8448
	s_waitcnt vmcnt(5)
	ds_write_b128 v211, v[106:109] offset:16896
	s_waitcnt vmcnt(4)
	ds_write_b128 v211, v[110:113] offset:25344
	s_waitcnt vmcnt(3)
	ds_write_b128 v211, v[114:117] offset:33792
	s_waitcnt vmcnt(2)
	ds_write_b128 v211, v[118:121] offset:42240
	s_waitcnt vmcnt(1)
	ds_write_b128 v211, v[130:133] offset:50688
	s_waitcnt vmcnt(0)
	ds_write_b128 v211, v[134:137] offset:59136
	v_mov_b32_e32 v98, v226
	s_waitcnt lgkmcnt(0)
	s_barrier
	ds_read_b128 v[130:133], v192
	s_waitcnt lgkmcnt(0)
	v_mfma_f32_16x16x32_bf16 v[66:69], v[62:65], v[130:133], v[66:69]
	ds_read_b128 v[130:133], v192 offset:64
	v_lshlrev_b32_e32 v98, 4, v98
	v_ashrrev_i32_e32 v99, 31, v98
	s_waitcnt lgkmcnt(0)
	v_mfma_f32_16x16x32_bf16 v[66:69], v[58:61], v[130:133], v[66:69]
	ds_read_b128 v[130:133], v192 offset:128
	v_lshl_add_u64 v[126:127], s[4:5], 0, v[98:99]
	v_add_co_u32_e32 v98, vcc, s33, v126
	s_waitcnt lgkmcnt(0)
	v_mfma_f32_16x16x32_bf16 v[66:69], v[54:57], v[130:133], v[66:69]
	ds_read_b128 v[130:133], v192 offset:192
	v_addc_co_u32_e32 v99, vcc, 0, v127, vcc
	s_waitcnt lgkmcnt(0)
	v_mfma_f32_16x16x32_bf16 v[66:69], v[50:53], v[130:133], v[66:69]
	ds_read_b128 v[130:133], v192 offset:256
	v_add_co_u32_e32 v102, vcc, s17, v126
	s_waitcnt lgkmcnt(0)
	v_mfma_f32_16x16x32_bf16 v[66:69], v[46:49], v[130:133], v[66:69]
	ds_read_b128 v[130:133], v192 offset:320
	v_addc_co_u32_e32 v103, vcc, 0, v127, vcc
	s_waitcnt lgkmcnt(0)
	v_mfma_f32_16x16x32_bf16 v[66:69], v[42:45], v[130:133], v[66:69]
	ds_read_b128 v[130:133], v192 offset:384
	v_add_co_u32_e32 v106, vcc, s18, v126
	s_waitcnt lgkmcnt(0)
	v_mfma_f32_16x16x32_bf16 v[66:69], v[38:41], v[130:133], v[66:69]
	ds_read_b128 v[130:133], v192 offset:448
	v_addc_co_u32_e32 v107, vcc, 0, v127, vcc
	s_waitcnt lgkmcnt(0)
	v_mfma_f32_16x16x32_bf16 v[66:69], v[34:37], v[130:133], v[66:69]
	ds_read_b128 v[130:133], v192 offset:8448
	v_add_co_u32_e32 v110, vcc, s20, v126
	s_waitcnt lgkmcnt(0)
	v_mfma_f32_16x16x32_bf16 v[70:73], v[62:65], v[130:133], v[70:73]
	ds_read_b128 v[130:133], v192 offset:8512
	v_addc_co_u32_e32 v111, vcc, 0, v127, vcc
	s_waitcnt lgkmcnt(0)
	v_mfma_f32_16x16x32_bf16 v[70:73], v[58:61], v[130:133], v[70:73]
	ds_read_b128 v[130:133], v192 offset:8576
	v_add_co_u32_e32 v114, vcc, s21, v126
	s_waitcnt lgkmcnt(0)
	v_mfma_f32_16x16x32_bf16 v[70:73], v[54:57], v[130:133], v[70:73]
	ds_read_b128 v[130:133], v192 offset:8640
	global_load_dwordx4 v[98:101], v[98:99], off
	v_addc_co_u32_e32 v115, vcc, 0, v127, vcc
	s_waitcnt lgkmcnt(0)
	v_mfma_f32_16x16x32_bf16 v[70:73], v[50:53], v[130:133], v[70:73]
	ds_read_b128 v[130:133], v192 offset:8704
	global_load_dwordx4 v[102:105], v[102:103], off
	v_add_co_u32_e32 v118, vcc, s22, v126
	s_waitcnt lgkmcnt(0)
	v_mfma_f32_16x16x32_bf16 v[70:73], v[46:49], v[130:133], v[70:73]
	ds_read_b128 v[130:133], v192 offset:8768
	global_load_dwordx4 v[106:109], v[106:107], off
	v_addc_co_u32_e32 v119, vcc, 0, v127, vcc
	s_waitcnt lgkmcnt(0)
	v_mfma_f32_16x16x32_bf16 v[70:73], v[42:45], v[130:133], v[70:73]
	ds_read_b128 v[130:133], v192 offset:8832
	global_load_dwordx4 v[110:113], v[110:111], off
	s_add_u32 s4, s0, s16
	s_waitcnt lgkmcnt(0)
	v_mfma_f32_16x16x32_bf16 v[70:73], v[38:41], v[130:133], v[70:73]
	ds_read_b128 v[130:133], v192 offset:8896
	global_load_dwordx4 v[114:117], v[114:115], off
	s_addc_u32 s5, s1, 0
	s_waitcnt lgkmcnt(0)
	v_mfma_f32_16x16x32_bf16 v[70:73], v[34:37], v[130:133], v[70:73]
	ds_read_b128 v[130:133], v192 offset:16896
	global_load_dwordx4 v[118:121], v[118:119], off
	s_lshl_b64 s[4:5], s[4:5], 9
	s_waitcnt lgkmcnt(0)
	v_mfma_f32_16x16x32_bf16 v[74:77], v[62:65], v[130:133], v[74:77]
	ds_read_b128 v[130:133], v192 offset:16960
	s_add_u32 s4, s78, s4
	s_addc_u32 s5, s79, s5
	s_waitcnt lgkmcnt(0)
	v_mfma_f32_16x16x32_bf16 v[74:77], v[58:61], v[130:133], v[74:77]
	ds_read_b128 v[130:133], v192 offset:17024
	ds_read_b128 v[134:137], v192 offset:17088
	ds_read_b128 v[138:141], v192 offset:17152
	ds_read_b128 v[142:145], v192 offset:17216
	s_waitcnt lgkmcnt(3)
	v_mfma_f32_16x16x32_bf16 v[74:77], v[54:57], v[130:133], v[74:77]
	ds_read_b128 v[130:133], v192 offset:17280
	s_waitcnt lgkmcnt(3)
	v_mfma_f32_16x16x32_bf16 v[74:77], v[50:53], v[134:137], v[74:77]
	ds_read_b128 v[134:137], v192 offset:17344
	s_waitcnt lgkmcnt(3)
	v_mfma_f32_16x16x32_bf16 v[74:77], v[46:49], v[138:141], v[74:77]
	ds_read_b128 v[138:141], v192 offset:25344
	s_waitcnt lgkmcnt(3)
	v_mfma_f32_16x16x32_bf16 v[74:77], v[42:45], v[142:145], v[74:77]
	ds_read_b128 v[142:145], v192 offset:25408
	s_waitcnt lgkmcnt(3)
; #define LAS __attribute__((address_space(3)))
; #define MFMA16(a, b, c) __builtin_amdgcn_mfma_f32_16x16x32_bf16((a), (b), (c), 0, 0, 0)
; __device__ void ret_out_phase(LAS unsigned char* lds, const bf16_t* PROJ, const bf16_t* ST, bf16_t* MIX, const float* lgf, const float* lgb, const float* ogain) {
;     ...
;             for (int i = 0; i < 8; ++i) *(LAS u32x4*)(buf + ((tid >> 5) + 16 * i) * RP + (tid & 31) * 16) = stg[i];
;             __syncthreads();
;     ...
;                 for (int ccl = 0; ccl < 8; ++ccl)
; #pragma unroll
;                     for (int ks = 0; ks < 8; ++ks) { const bf16x8 bfrag = *(const LAS bf16x8*)(buf + (16 * ccl + fr) * RP + (32 * ks + 8 * g) * 2); o[(s & 1) * 8 + ccl] = MFMA16(qf[ks], bfrag, o[(s & 1) * 8 + ccl]); }
	v_mfma_f32_16x16x32_bf16 v[74:77], v[38:41], v[130:133], v[74:77]
	ds_read_b128 v[130:133], v192 offset:25472
	s_waitcnt lgkmcnt(3)
	v_mfma_f32_16x16x32_bf16 v[74:77], v[34:37], v[134:137], v[74:77]
	ds_read_b128 v[134:137], v192 offset:25536
	s_waitcnt lgkmcnt(3)
	v_mfma_f32_16x16x32_bf16 v[78:81], v[62:65], v[138:141], v[78:81]
	ds_read_b128 v[138:141], v192 offset:25600
	s_waitcnt lgkmcnt(3)
	v_mfma_f32_16x16x32_bf16 v[78:81], v[58:61], v[142:145], v[78:81]
	ds_read_b128 v[142:145], v192 offset:25664
	s_waitcnt lgkmcnt(3)
	v_mfma_f32_16x16x32_bf16 v[78:81], v[54:57], v[130:133], v[78:81]
	ds_read_b128 v[130:133], v192 offset:25728
	s_waitcnt lgkmcnt(3)
	v_mfma_f32_16x16x32_bf16 v[78:81], v[50:53], v[134:137], v[78:81]
	ds_read_b128 v[134:137], v192 offset:25792
	s_waitcnt lgkmcnt(3)
	v_mfma_f32_16x16x32_bf16 v[78:81], v[46:49], v[138:141], v[78:81]
	ds_read_b128 v[138:141], v192 offset:33792
	s_waitcnt lgkmcnt(3)
	v_mfma_f32_16x16x32_bf16 v[78:81], v[42:45], v[142:145], v[78:81]
	ds_read_b128 v[142:145], v192 offset:33856
	s_waitcnt lgkmcnt(3)
	v_mfma_f32_16x16x32_bf16 v[78:81], v[38:41], v[130:133], v[78:81]
	ds_read_b128 v[130:133], v192 offset:33920
	s_waitcnt lgkmcnt(3)
	v_mfma_f32_16x16x32_bf16 v[78:81], v[34:37], v[134:137], v[78:81]
	ds_read_b128 v[134:137], v192 offset:33984
	s_waitcnt lgkmcnt(3)
	v_mfma_f32_16x16x32_bf16 v[82:85], v[62:65], v[138:141], v[82:85]
	ds_read_b128 v[138:141], v192 offset:34048
	s_waitcnt lgkmcnt(3)
	v_mfma_f32_16x16x32_bf16 v[82:85], v[58:61], v[142:145], v[82:85]
	ds_read_b128 v[142:145], v192 offset:34112
	s_waitcnt lgkmcnt(3)
	v_mfma_f32_16x16x32_bf16 v[82:85], v[54:57], v[130:133], v[82:85]
	ds_read_b128 v[130:133], v192 offset:34176
	s_waitcnt lgkmcnt(3)
	v_mfma_f32_16x16x32_bf16 v[82:85], v[50:53], v[134:137], v[82:85]
	ds_read_b128 v[134:137], v192 offset:34240
	s_waitcnt lgkmcnt(3)
	v_mfma_f32_16x16x32_bf16 v[82:85], v[46:49], v[138:141], v[82:85]
	ds_read_b128 v[138:141], v192 offset:42240
	s_waitcnt lgkmcnt(3)
	v_mfma_f32_16x16x32_bf16 v[82:85], v[42:45], v[142:145], v[82:85]
	ds_read_b128 v[142:145], v192 offset:42304
	s_waitcnt lgkmcnt(3)
	v_mfma_f32_16x16x32_bf16 v[82:85], v[38:41], v[130:133], v[82:85]
	ds_read_b128 v[130:133], v192 offset:42368
	s_waitcnt lgkmcnt(3)
	v_mfma_f32_16x16x32_bf16 v[82:85], v[34:37], v[134:137], v[82:85]
	ds_read_b128 v[134:137], v192 offset:42432
	s_waitcnt lgkmcnt(3)
	v_mfma_f32_16x16x32_bf16 v[86:89], v[62:65], v[138:141], v[86:89]
	ds_read_b128 v[138:141], v192 offset:42496
	s_waitcnt lgkmcnt(3)
	v_mfma_f32_16x16x32_bf16 v[86:89], v[58:61], v[142:145], v[86:89]
	ds_read_b128 v[142:145], v192 offset:42560
	s_waitcnt lgkmcnt(3)
	v_mfma_f32_16x16x32_bf16 v[86:89], v[54:57], v[130:133], v[86:89]
	ds_read_b128 v[130:133], v192 offset:42624
	s_waitcnt lgkmcnt(3)
	v_mfma_f32_16x16x32_bf16 v[86:89], v[50:53], v[134:137], v[86:89]
	ds_read_b128 v[134:137], v192 offset:42688
	s_waitcnt lgkmcnt(3)
	v_mfma_f32_16x16x32_bf16 v[86:89], v[46:49], v[138:141], v[86:89]
	s_waitcnt lgkmcnt(2)
	v_mfma_f32_16x16x32_bf16 v[86:89], v[42:45], v[142:145], v[86:89]
	s_waitcnt lgkmcnt(1)
	v_mfma_f32_16x16x32_bf16 v[86:89], v[38:41], v[130:133], v[86:89]
	s_waitcnt lgkmcnt(0)
	v_mfma_f32_16x16x32_bf16 v[86:89], v[34:37], v[134:137], v[86:89]
	ds_read_b128 v[130:133], v192 offset:50688
	v_mfma_f32_16x16x32_bf16 v[30:33], v[34:37], v[122:125], v[30:33]
	v_add_co_u32_e32 v122, vcc, s23, v126
	s_nop 1
	v_addc_co_u32_e32 v123, vcc, 0, v127, vcc
	v_add_co_u32_e32 v126, vcc, s24, v126
	global_load_dwordx4 v[122:125], v[122:123], off
	s_nop 0
	v_addc_co_u32_e32 v127, vcc, 0, v127, vcc
	s_waitcnt lgkmcnt(0)
	v_mfma_f32_16x16x32_bf16 v[90:93], v[62:65], v[130:133], v[90:93]
	ds_read_b128 v[130:133], v192 offset:50752
	global_load_dwordx4 v[126:129], v[126:127], off
	s_waitcnt lgkmcnt(0)
	v_mfma_f32_16x16x32_bf16 v[90:93], v[58:61], v[130:133], v[90:93]
	ds_read_b128 v[130:133], v192 offset:50816
	ds_read_b128 v[134:137], v192 offset:50880
	ds_read_b128 v[138:141], v192 offset:50944
	ds_read_b128 v[142:145], v192 offset:51008
	s_waitcnt lgkmcnt(3)
	v_mfma_f32_16x16x32_bf16 v[90:93], v[54:57], v[130:133], v[90:93]
	ds_read_b128 v[130:133], v192 offset:51072
	s_waitcnt lgkmcnt(3)
	v_mfma_f32_16x16x32_bf16 v[90:93], v[50:53], v[134:137], v[90:93]
	ds_read_b128 v[134:137], v192 offset:51136
	s_waitcnt lgkmcnt(3)
	v_mfma_f32_16x16x32_bf16 v[90:93], v[46:49], v[138:141], v[90:93]
	ds_read_b128 v[138:141], v192 offset:59136
	s_waitcnt lgkmcnt(3)
	v_mfma_f32_16x16x32_bf16 v[90:93], v[42:45], v[142:145], v[90:93]
	ds_read_b128 v[142:145], v192 offset:59200
	s_waitcnt lgkmcnt(3)
	v_mfma_f32_16x16x32_bf16 v[90:93], v[38:41], v[130:133], v[90:93]
	ds_read_b128 v[130:133], v192 offset:59264
	s_waitcnt lgkmcnt(3)
	v_mfma_f32_16x16x32_bf16 v[90:93], v[34:37], v[134:137], v[90:93]
	ds_read_b128 v[134:137], v192 offset:59328
	s_waitcnt lgkmcnt(3)
	v_mfma_f32_16x16x32_bf16 v[94:97], v[62:65], v[138:141], v[94:97]
	ds_read_b128 v[138:141], v192 offset:59392
	s_waitcnt lgkmcnt(3)
	v_mfma_f32_16x16x32_bf16 v[94:97], v[58:61], v[142:145], v[94:97]
	ds_read_b128 v[142:145], v192 offset:59456
	s_waitcnt lgkmcnt(3)
	v_mfma_f32_16x16x32_bf16 v[94:97], v[54:57], v[130:133], v[94:97]
	ds_read_b128 v[130:133], v192 offset:59520
	s_waitcnt lgkmcnt(3)
	v_mfma_f32_16x16x32_bf16 v[94:97], v[50:53], v[134:137], v[94:97]
	s_waitcnt lgkmcnt(2)
	v_mfma_f32_16x16x32_bf16 v[94:97], v[46:49], v[138:141], v[94:97]
	s_waitcnt lgkmcnt(1)
	v_mfma_f32_16x16x32_bf16 v[94:97], v[42:45], v[142:145], v[94:97]
	s_waitcnt lgkmcnt(0)
	v_mfma_f32_16x16x32_bf16 v[94:97], v[38:41], v[130:133], v[94:97]
	ds_read_b128 v[130:133], v192 offset:59584
	s_waitcnt vmcnt(7)
	ds_write_b128 v210, v[98:101]
	s_waitcnt vmcnt(6)
	ds_write_b128 v210, v[102:105] offset:8448
	s_waitcnt vmcnt(5)
	ds_write_b128 v210, v[106:109] offset:16896
	s_waitcnt vmcnt(4)
	ds_write_b128 v210, v[110:113] offset:25344
	s_waitcnt vmcnt(3)
	ds_write_b128 v210, v[114:117] offset:33792
	s_waitcnt vmcnt(2)
	ds_write_b128 v210, v[118:121] offset:42240
	s_waitcnt vmcnt(1)
	ds_write_b128 v210, v[122:125] offset:50688
	s_waitcnt vmcnt(0)
	ds_write_b128 v210, v[126:129] offset:59136
	v_mov_b32_e32 v98, v226
	s_waitcnt lgkmcnt(8)
	v_mfma_f32_16x16x32_bf16 v[94:97], v[34:37], v[130:133], v[94:97]
	s_waitcnt lgkmcnt(0)
	s_barrier
; #define LAS __attribute__((address_space(3)))
; #define MFMA16(a, b, c) __builtin_amdgcn_mfma_f32_16x16x32_bf16((a), (b), (c), 0, 0, 0)
; __device__ void ret_out_phase(LAS unsigned char* lds, const bf16_t* PROJ, const bf16_t* ST, bf16_t* MIX, const float* lgf, const float* lgb, const float* ogain) {
;     ...
;                 for (int kt = 0; kt < 8; ++kt) { st[kt] = (f32x4){0.f, 0.f, 0.f, 0.f};
; #pragma unroll
;                     for (int ks = 0; ks < 8; ++ks) { const bf16x8 af = *(const LAS bf16x8*)(buf + (16 * kt + fr) * RP + (32 * ks + 8 * g) * 2); st[kt] = MFMA16(af, qf[ks], st[kt]); } }
	ds_read_b128 v[130:133], v191
	ds_read_b128 v[134:137], v191 offset:64
	s_waitcnt lgkmcnt(1)
	v_mfma_f32_16x16x32_bf16 v[130:133], v[130:133], v[62:65], 0
	ds_read_b128 v[138:141], v191 offset:25408
	ds_read_b128 v[142:145], v191 offset:42304
	ds_read_b128 v[212:215], v191 offset:59200
	s_waitcnt lgkmcnt(3)
	v_mfma_f32_16x16x32_bf16 v[130:133], v[134:137], v[58:61], v[130:133]
	ds_read_b128 v[134:137], v191 offset:128
	v_lshlrev_b32_e32 v98, 4, v98
	v_ashrrev_i32_e32 v99, 31, v98
	s_waitcnt lgkmcnt(0)
	v_mfma_f32_16x16x32_bf16 v[130:133], v[134:137], v[54:57], v[130:133]
	ds_read_b128 v[134:137], v191 offset:192
	v_lshl_add_u64 v[126:127], s[4:5], 0, v[98:99]
	v_add_co_u32_e32 v98, vcc, s33, v126
	s_waitcnt lgkmcnt(0)
	v_mfma_f32_16x16x32_bf16 v[130:133], v[134:137], v[50:53], v[130:133]
	ds_read_b128 v[134:137], v191 offset:256
	v_addc_co_u32_e32 v99, vcc, 0, v127, vcc
	s_waitcnt lgkmcnt(0)
	v_mfma_f32_16x16x32_bf16 v[130:133], v[134:137], v[46:49], v[130:133]
	ds_read_b128 v[134:137], v191 offset:320
	v_add_co_u32_e32 v102, vcc, s17, v126
	s_waitcnt lgkmcnt(0)
	v_mfma_f32_16x16x32_bf16 v[130:133], v[134:137], v[42:45], v[130:133]
	ds_read_b128 v[134:137], v191 offset:384
	v_addc_co_u32_e32 v103, vcc, 0, v127, vcc
	s_waitcnt lgkmcnt(0)
	v_mfma_f32_16x16x32_bf16 v[130:133], v[134:137], v[38:41], v[130:133]
	ds_read_b128 v[134:137], v191 offset:448
	v_add_co_u32_e32 v106, vcc, s18, v126
	s_waitcnt lgkmcnt(0)
	v_mfma_f32_16x16x32_bf16 v[154:157], v[134:137], v[34:37], v[130:133]
	s_nop 3
	ds_read_b128 v[130:133], v191 offset:8448
	ds_read_b128 v[134:137], v191 offset:8512
	v_addc_co_u32_e32 v107, vcc, 0, v127, vcc
	s_waitcnt lgkmcnt(1)
	v_mfma_f32_16x16x32_bf16 v[130:133], v[130:133], v[62:65], 0
	v_add_co_u32_e32 v110, vcc, s20, v126
	global_load_dwordx4 v[98:101], v[98:99], off
	s_waitcnt lgkmcnt(0)
	v_mfma_f32_16x16x32_bf16 v[130:133], v[134:137], v[58:61], v[130:133]
	ds_read_b128 v[134:137], v191 offset:8576
	v_addc_co_u32_e32 v111, vcc, 0, v127, vcc
	s_waitcnt lgkmcnt(0)
	v_mfma_f32_16x16x32_bf16 v[130:133], v[134:137], v[54:57], v[130:133]
	ds_read_b128 v[134:137], v191 offset:8640
	v_add_co_u32_e32 v114, vcc, s21, v126
	s_waitcnt lgkmcnt(0)
	v_mfma_f32_16x16x32_bf16 v[130:133], v[134:137], v[50:53], v[130:133]
	ds_read_b128 v[134:137], v191 offset:8704
	v_addc_co_u32_e32 v115, vcc, 0, v127, vcc
	s_waitcnt lgkmcnt(0)
	v_mfma_f32_16x16x32_bf16 v[130:133], v[134:137], v[46:49], v[130:133]
	ds_read_b128 v[134:137], v191 offset:8768
	v_add_co_u32_e32 v118, vcc, s22, v126
	s_waitcnt lgkmcnt(0)
	v_mfma_f32_16x16x32_bf16 v[130:133], v[134:137], v[42:45], v[130:133]
	ds_read_b128 v[134:137], v191 offset:8832
	v_addc_co_u32_e32 v119, vcc, 0, v127, vcc
	s_waitcnt lgkmcnt(0)
	v_mfma_f32_16x16x32_bf16 v[130:133], v[134:137], v[38:41], v[130:133]
	ds_read_b128 v[134:137], v191 offset:8896
	v_add_co_u32_e32 v122, vcc, s23, v126
	s_waitcnt lgkmcnt(0)
	v_mfma_f32_16x16x32_bf16 v[158:161], v[134:137], v[34:37], v[130:133]
	s_nop 3
	ds_read_b128 v[130:133], v191 offset:16896
	ds_read_b128 v[134:137], v191 offset:16960
	v_addc_co_u32_e32 v123, vcc, 0, v127, vcc
	s_waitcnt lgkmcnt(1)
	v_mfma_f32_16x16x32_bf16 v[130:133], v[130:133], v[62:65], 0
	v_add_co_u32_e32 v126, vcc, s24, v126
	global_load_dwordx4 v[102:105], v[102:103], off
	s_waitcnt lgkmcnt(0)
	v_mfma_f32_16x16x32_bf16 v[130:133], v[134:137], v[58:61], v[130:133]
	ds_read_b128 v[134:137], v191 offset:17024
	v_addc_co_u32_e32 v127, vcc, 0, v127, vcc
	s_waitcnt lgkmcnt(0)
	v_mfma_f32_16x16x32_bf16 v[130:133], v[134:137], v[54:57], v[130:133]
	ds_read_b128 v[134:137], v191 offset:17088
	global_load_dwordx4 v[106:109], v[106:107], off
	v_cmp_gt_i32_e32 vcc, 1, v173
	s_waitcnt lgkmcnt(0)
	v_mfma_f32_16x16x32_bf16 v[130:133], v[134:137], v[50:53], v[130:133]
	ds_read_b128 v[134:137], v191 offset:17152
	global_load_dwordx4 v[110:113], v[110:111], off
	s_waitcnt lgkmcnt(0)
	v_mfma_f32_16x16x32_bf16 v[130:133], v[134:137], v[46:49], v[130:133]
	ds_read_b128 v[134:137], v191 offset:17216
	global_load_dwordx4 v[114:117], v[114:115], off
	s_nop 0
	global_load_dwordx4 v[118:121], v[118:119], off
	s_waitcnt lgkmcnt(0)
	v_mfma_f32_16x16x32_bf16 v[130:133], v[134:137], v[42:45], v[130:133]
	ds_read_b128 v[134:137], v191 offset:17280
	global_load_dwordx4 v[122:125], v[122:123], off
	s_nop 0
	global_load_dwordx4 v[126:129], v[126:127], off
	s_waitcnt lgkmcnt(0)
	v_mfma_f32_16x16x32_bf16 v[130:133], v[134:137], v[38:41], v[130:133]
	ds_read_b128 v[134:137], v191 offset:17344
	s_waitcnt lgkmcnt(0)
	v_mfma_f32_16x16x32_bf16 v[130:133], v[134:137], v[34:37], v[130:133]
	ds_read_b128 v[134:137], v191 offset:25344
	s_waitcnt lgkmcnt(0)
	v_mfma_f32_16x16x32_bf16 v[134:137], v[134:137], v[62:65], 0
	v_mfma_f32_16x16x32_bf16 v[134:137], v[138:141], v[58:61], v[134:137]
	ds_read_b128 v[138:141], v191 offset:25472
	ds_read_b128 v[146:149], v191 offset:25536
	s_waitcnt lgkmcnt(1)
	v_mfma_f32_16x16x32_bf16 v[134:137], v[138:141], v[54:57], v[134:137]
	ds_read_b128 v[138:141], v191 offset:25600
	s_waitcnt lgkmcnt(1)
; #define LAS __attribute__((address_space(3)))
; #define MFMA16(a, b, c) __builtin_amdgcn_mfma_f32_16x16x32_bf16((a), (b), (c), 0, 0, 0)
; __device__ void ret_out_phase(LAS unsigned char* lds, const bf16_t* PROJ, const bf16_t* ST, bf16_t* MIX, const float* lgf, const float* lgb, const float* ogain) {
;     ...
;                 for (int kt = 0; kt < 8; ++kt) { st[kt] = (f32x4){0.f, 0.f, 0.f, 0.f};
; #pragma unroll
;                     for (int ks = 0; ks < 8; ++ks) { const bf16x8 af = *(const LAS bf16x8*)(buf + (16 * kt + fr) * RP + (32 * ks + 8 * g) * 2); st[kt] = MFMA16(af, qf[ks], st[kt]); } }
;                 const int ql = half * 128 + 16 * wave + fr;
; #pragma unroll
;                 for (int kt = 0; kt < 8; ++kt)
; #pragma unroll
;                     for (int j = 0; j < 4; ++j) { const int kl = kt2 * 128 + 16 * kt + 4 * g + j; const int d = ql - kl;
;                         const float w = d > 0 ? __expf(lf * (float)d) : (d < 0 ? __expf(lb * (float)(-d)) : 2.0f); st[kt][j] *= w; }
	v_mfma_f32_16x16x32_bf16 v[134:137], v[146:149], v[50:53], v[134:137]
	ds_read_b128 v[146:149], v191 offset:25664
	s_waitcnt lgkmcnt(1)
	v_mfma_f32_16x16x32_bf16 v[134:137], v[138:141], v[46:49], v[134:137]
	ds_read_b128 v[138:141], v191 offset:25728
	s_waitcnt lgkmcnt(1)
	v_mfma_f32_16x16x32_bf16 v[134:137], v[146:149], v[42:45], v[134:137]
	ds_read_b128 v[146:149], v191 offset:25792
	s_waitcnt lgkmcnt(1)
	v_mfma_f32_16x16x32_bf16 v[134:137], v[138:141], v[38:41], v[134:137]
	s_waitcnt lgkmcnt(0)
	v_mfma_f32_16x16x32_bf16 v[150:153], v[146:149], v[34:37], v[134:137]
	s_nop 4
	ds_read_b128 v[134:137], v191 offset:33792
	ds_read_b128 v[138:141], v191 offset:33856
	s_waitcnt lgkmcnt(1)
	v_mfma_f32_16x16x32_bf16 v[134:137], v[134:137], v[62:65], 0
	s_waitcnt lgkmcnt(0)
	v_mfma_f32_16x16x32_bf16 v[134:137], v[138:141], v[58:61], v[134:137]
	ds_read_b128 v[138:141], v191 offset:33920
	ds_read_b128 v[146:149], v191 offset:33984
	s_waitcnt lgkmcnt(1)
	v_mfma_f32_16x16x32_bf16 v[134:137], v[138:141], v[54:57], v[134:137]
	ds_read_b128 v[138:141], v191 offset:34048
	s_waitcnt lgkmcnt(1)
	v_mfma_f32_16x16x32_bf16 v[134:137], v[146:149], v[50:53], v[134:137]
	ds_read_b128 v[146:149], v191 offset:34112
	s_waitcnt lgkmcnt(1)
	v_mfma_f32_16x16x32_bf16 v[134:137], v[138:141], v[46:49], v[134:137]
	ds_read_b128 v[138:141], v191 offset:34176
	s_waitcnt lgkmcnt(1)
	v_mfma_f32_16x16x32_bf16 v[134:137], v[146:149], v[42:45], v[134:137]
	ds_read_b128 v[146:149], v191 offset:34240
	s_waitcnt lgkmcnt(1)
	v_mfma_f32_16x16x32_bf16 v[134:137], v[138:141], v[38:41], v[134:137]
	s_waitcnt lgkmcnt(0)
	v_mfma_f32_16x16x32_bf16 v[134:137], v[146:149], v[34:37], v[134:137]
	ds_read_b128 v[138:141], v191 offset:42240
	s_waitcnt lgkmcnt(0)
	v_mfma_f32_16x16x32_bf16 v[138:141], v[138:141], v[62:65], 0
	v_mfma_f32_16x16x32_bf16 v[138:141], v[142:145], v[58:61], v[138:141]
	ds_read_b128 v[142:145], v191 offset:42368
	s_waitcnt lgkmcnt(0)
	v_mfma_f32_16x16x32_bf16 v[138:141], v[142:145], v[54:57], v[138:141]
	ds_read_b128 v[142:145], v191 offset:42432
	s_waitcnt lgkmcnt(0)
	v_mfma_f32_16x16x32_bf16 v[138:141], v[142:145], v[50:53], v[138:141]
	ds_read_b128 v[142:145], v191 offset:42496
	s_waitcnt lgkmcnt(0)
	v_mfma_f32_16x16x32_bf16 v[138:141], v[142:145], v[46:49], v[138:141]
	ds_read_b128 v[142:145], v191 offset:42560
	s_waitcnt lgkmcnt(0)
	v_mfma_f32_16x16x32_bf16 v[138:141], v[142:145], v[42:45], v[138:141]
	ds_read_b128 v[142:145], v191 offset:42624
	s_waitcnt lgkmcnt(0)
	v_mfma_f32_16x16x32_bf16 v[138:141], v[142:145], v[38:41], v[138:141]
	ds_read_b128 v[142:145], v191 offset:42688
	s_waitcnt lgkmcnt(0)
	v_mfma_f32_16x16x32_bf16 v[146:149], v[142:145], v[34:37], v[138:141]
	s_nop 4
	ds_read_b128 v[138:141], v191 offset:50688
	ds_read_b128 v[142:145], v191 offset:50752
	s_waitcnt lgkmcnt(1)
	v_mfma_f32_16x16x32_bf16 v[138:141], v[138:141], v[62:65], 0
	s_waitcnt lgkmcnt(0)
	v_mfma_f32_16x16x32_bf16 v[138:141], v[142:145], v[58:61], v[138:141]
	ds_read_b128 v[142:145], v191 offset:50816
	s_waitcnt lgkmcnt(0)
	v_mfma_f32_16x16x32_bf16 v[138:141], v[142:145], v[54:57], v[138:141]
	ds_read_b128 v[142:145], v191 offset:50880
	s_waitcnt lgkmcnt(0)
	v_mfma_f32_16x16x32_bf16 v[138:141], v[142:145], v[50:53], v[138:141]
	ds_read_b128 v[142:145], v191 offset:50944
	s_waitcnt lgkmcnt(0)
	v_mfma_f32_16x16x32_bf16 v[138:141], v[142:145], v[46:49], v[138:141]
	ds_read_b128 v[142:145], v191 offset:51008
	s_waitcnt lgkmcnt(0)
	v_mfma_f32_16x16x32_bf16 v[138:141], v[142:145], v[42:45], v[138:141]
	ds_read_b128 v[142:145], v191 offset:51072
	s_waitcnt lgkmcnt(0)
	v_mfma_f32_16x16x32_bf16 v[138:141], v[142:145], v[38:41], v[138:141]
	ds_read_b128 v[142:145], v191 offset:51136
	s_waitcnt lgkmcnt(0)
	v_mfma_f32_16x16x32_bf16 v[138:141], v[142:145], v[34:37], v[138:141]
	ds_read_b128 v[142:145], v191 offset:59136
	s_waitcnt lgkmcnt(0)
	v_mfma_f32_16x16x32_bf16 v[142:145], v[142:145], v[62:65], 0
	v_mfma_f32_16x16x32_bf16 v[142:145], v[212:215], v[58:61], v[142:145]
	ds_read_b128 v[212:215], v191 offset:59264
	s_waitcnt lgkmcnt(0)
	v_mfma_f32_16x16x32_bf16 v[142:145], v[212:215], v[54:57], v[142:145]
	ds_read_b128 v[212:215], v191 offset:59328
	s_waitcnt lgkmcnt(0)
	v_mfma_f32_16x16x32_bf16 v[142:145], v[212:215], v[50:53], v[142:145]
	ds_read_b128 v[212:215], v191 offset:59392
	s_waitcnt lgkmcnt(0)
	v_mfma_f32_16x16x32_bf16 v[142:145], v[212:215], v[46:49], v[142:145]
	ds_read_b128 v[212:215], v191 offset:59456
	s_waitcnt lgkmcnt(0)
	v_mfma_f32_16x16x32_bf16 v[142:145], v[212:215], v[42:45], v[142:145]
	ds_read_b128 v[212:215], v191 offset:59520
	s_waitcnt lgkmcnt(0)
	v_mfma_f32_16x16x32_bf16 v[142:145], v[212:215], v[38:41], v[142:145]
	ds_read_b128 v[212:215], v191 offset:59584
	s_waitcnt lgkmcnt(0)
	v_mfma_f32_16x16x32_bf16 v[142:145], v[212:215], v[34:37], v[142:145]
	s_and_saveexec_b64 s[4:5], vcc
	s_xor_b64 s[4:5], exec, s[4:5]
	s_cbranch_execz .LBB0_37
	v_sub_u32_e32 v173, 0, v173
	v_cvt_f32_u32_e32 v173, v173
	v_cmp_ne_u32_e32 vcc, v0, v190
	v_mul_f32_e32 v173, v185, v173
	v_mul_f32_e32 v173, 0x3fb8aa3b, v173
	v_exp_f32_e32 v173, v173
	s_nop 0
	v_cndmask_b32_e32 v177, 2.0, v173, vcc

; #define LAS __attribute__((address_space(3)))
; __device__ void attn_phase(LAS unsigned char* lds, const bf16_t* PROJ, bf16_t* AP, float* LSE) {
;     ...
;     for (; item < 4608; item += gridDim.x) {
;         const AttnItem a = attn_decode(item);
;         const int pat = a.pat, h = a.h, dsh = a.dsh, start = a.start, L = a.L, r = a.r, b = a.b;
; #pragma unroll
;         for (int it = 0; it < 8; ++it) { const int idx = tid + 512 * it, row = idx >> 4, ch = idx & 15; *(LAS u32x4*)(Kl + row * KP + ch * 16) = kreg[it]; *(LAS u32x4*)(Vl + row * KP + ch * 16) = vreg[it]; }
;         const int qi = 128 * b + 16 * wave + fr; const size_t qtok = (size_t)(start + r + (qi << dsh));
;         bf16x8 qf[4];
; #pragma unroll
;         for (int ks = 0; ks < 4; ++ks) qf[ks] = *(const bf16x8*)(PROJ + pj(qtok, h * 128 + 32 * ks + 8 * g));
;         __syncthreads();
;         if (item + (int)gridDim.x < 4608) { const AttnItem an = attn_decode(item + gridDim.x); ATTN_ISSUE(an); }
.LBB0_339:
	s_lshl_b32 s12, s16, 1
	s_lshr_b32 s4, s0, s12
	s_lshr_b32 s0, s4, 7
	s_ff1_i32_b32 s1, s0
	s_add_i32 s0, s0, -1
	s_and_b32 s0, s0, s3
	s_lshl_b32 s14, s0, 7
	s_add_i32 s14, s14, s7
	s_lshr_b32 s15, s3, s1
	v_or_b32_e32 v0, s14, v130
	s_add_i32 s15, s15, s2
	v_lshlrev_b32_e32 v0, s12, v0
	s_and_b32 s13, s6, 7
	v_add_u32_e32 v128, s15, v0
	v_ashrrev_i32_e32 v129, 31, v128
	s_mul_i32 s60, s13, 0x6000
	v_lshl_add_u64 v[2:3], v[128:129], 0, s[60:61]
	v_lshlrev_b64 v[2:3], 8, v[2:3]
	v_lshl_add_u64 v[2:3], v[118:119], 0, v[2:3]
	global_load_dwordx4 v[80:83], v[2:3], off
	global_load_dwordx4 v[76:79], v[2:3], off offset:64
	global_load_dwordx4 v[72:75], v[2:3], off offset:128
	global_load_dwordx4 v[68:71], v[2:3], off offset:192
	v_add_u32_e32 v0, v131, v138
	s_waitcnt vmcnt(9)
	ds_write_b128 v0, v[8:11]
	v_add_u32_e32 v0, v132, v138
	ds_write_b128 v0, v[4:7]
	v_add_u32_e32 v0, v131, v140
	s_waitcnt vmcnt(7)
	ds_write_b128 v0, v[16:19]
	v_add_u32_e32 v0, v132, v140
	ds_write_b128 v0, v[12:15]
	v_add_u32_e32 v0, v131, v142
	s_waitcnt vmcnt(5)
	ds_write_b128 v0, v[24:27]
	v_add_u32_e32 v0, v132, v142
	ds_write_b128 v0, v[20:23]
	v_add_u32_e32 v0, v131, v144
	s_waitcnt vmcnt(4)
	ds_write_b128 v0, v[32:35]
	v_add_u32_e32 v0, v132, v144
	ds_write_b128 v0, v[28:31]
	v_add_u32_e32 v0, v131, v146
	ds_write_b128 v0, v[36:39]
	v_add_u32_e32 v0, v132, v146
	ds_write_b128 v0, v[40:43]
	v_add_u32_e32 v0, v131, v148
	ds_write_b128 v0, v[44:47]
	v_add_u32_e32 v0, v132, v148
	ds_write_b128 v0, v[48:51]
	v_add_u32_e32 v0, v131, v150
	s_add_i32 s6, s6, s10
	ds_write_b128 v0, v[52:55]
	v_add_u32_e32 v0, v132, v150
	s_cmpk_gt_i32 s6, 0x11ff
	ds_write_b128 v0, v[56:59]
	v_add_u32_e32 v0, v131, v152
	s_cselect_b64 s[0:1], -1, 0
	ds_write_b128 v0, v[60:63]
	v_add_u32_e32 v0, v132, v152
	s_and_b64 vcc, exec, s[0:1]
	ds_write_b128 v0, v[64:67]
	s_waitcnt lgkmcnt(0)
	s_barrier
	s_waitcnt vmcnt(0)
	s_cbranch_vccnz .LBB0_362
	s_ashr_i32 s5, s6, 8
	s_cmp_lt_i32 s5, 6
	s_mov_b32 s2, 0
	s_cbranch_scc1 .LBB0_342
	s_lshr_b32 s2, s6, 8
	s_add_i32 s3, s2, 0xfffa
	s_and_b32 s2, s3, 0xff
	s_mulk_i32 s2, 0xab
	s_bfe_u32 s5, s2, 0x70009
	s_add_i32 s2, s5, 1
	s_mul_i32 s5, s5, 3
	s_sub_i32 s3, s3, s5
	s_and_b32 s2, s2, 0xff
	s_and_b32 s5, s3, 0xff

; #define LAS __attribute__((address_space(3)))
; #define MFMA16(a, b, c) __builtin_amdgcn_mfma_f32_16x16x32_bf16((a), (b), (c), 0, 0, 0)
; __device__ void attn_phase(LAS unsigned char* lds, const bf16_t* PROJ, bf16_t* AP, float* LSE) {
;     ...
;         for (int kt = 0; kt < 9; ++kt) { st[kt] = (f32x4){0.f, 0.f, 0.f, 0.f};
; #pragma unroll
;             for (int ks = 0; ks < 4; ++ks) { const bf16x8 af = *(const LAS bf16x8*)(Kl + (16 * wave + 16 * kt + fr) * KP + (32 * ks + 8 * g) * 2); st[kt] = MFMA16(af, qf[ks], st[kt]); } }
;         const float sc = 0.08838834764831845f * 1.4426950408889634f;
;         float mx = -1e30f;
; #pragma unroll
;         for (int kt = 0; kt < 9; ++kt)
; #pragma unroll
;             for (int j = 0; j < 4; ++j) { const int dd = -64 + 16 * kt + 4 * g + j - fr; const int ki = 128 * b - 64 + 16 * wave + 16 * kt + 4 * g + j;
;                 const bool valid = (dd >= -64) && (dd <= 64) && (ki >= 0) && (ki < L); const float tv = valid ? st[kt][j] * sc : -1e30f; st[kt][j] = tv; mx = fmaxf(mx, tv); }
.LBB0_362:
	ds_read_b128 v[84:87], v165
	ds_read_b128 v[88:91], v165 offset:64
	s_sub_i32 s2, s14, 64
	v_or_b32_e32 v0, s2, v133
	s_cmp_gt_i32 s2, -1
	v_cmp_gt_i32_e32 vcc, s4, v0
	s_cselect_b64 s[20:21], -1, 0
	s_and_b64 s[22:23], s[40:41], vcc
	s_and_b64 vcc, s[20:21], s[22:23]
	s_waitcnt lgkmcnt(1)
	v_mfma_f32_16x16x32_bf16 v[84:87], v[84:87], v[80:83], 0
	v_or_b32_e32 v3, 2, v0
	s_mov_b32 s3, 0xf149f2ca
	ds_read_b128 v[180:183], v172 offset:64
	s_waitcnt lgkmcnt(1)
	v_mfma_f32_16x16x32_bf16 v[84:87], v[88:91], v[76:79], v[84:87]
	ds_read_b128 v[88:91], v165 offset:128
	s_waitcnt lgkmcnt(0)
	v_mfma_f32_16x16x32_bf16 v[84:87], v[88:91], v[72:75], v[84:87]
	ds_read_b128 v[88:91], v165 offset:192
	s_waitcnt lgkmcnt(0)
	v_mfma_f32_16x16x32_bf16 v[112:115], v[88:91], v[68:71], v[84:87]
	s_nop 4
	ds_read_b128 v[84:87], v166
	ds_read_b128 v[88:91], v166 offset:64
	s_nop 0
	v_mul_f32_e32 v2, 0x3e0293ee, v112
	s_waitcnt lgkmcnt(1)
	v_mfma_f32_16x16x32_bf16 v[84:87], v[84:87], v[80:83], 0
	s_waitcnt lgkmcnt(0)
	v_mfma_f32_16x16x32_bf16 v[84:87], v[88:91], v[76:79], v[84:87]
	ds_read_b128 v[88:91], v166 offset:128
	s_waitcnt lgkmcnt(0)
	v_mfma_f32_16x16x32_bf16 v[84:87], v[88:91], v[72:75], v[84:87]
	ds_read_b128 v[88:91], v166 offset:192
	s_waitcnt lgkmcnt(0)
	v_mfma_f32_16x16x32_bf16 v[108:111], v[88:91], v[68:71], v[84:87]
	s_nop 4
	ds_read_b128 v[84:87], v167
	ds_read_b128 v[88:91], v167 offset:64
	s_waitcnt lgkmcnt(1)
	v_mfma_f32_16x16x32_bf16 v[84:87], v[84:87], v[80:83], 0
	s_waitcnt lgkmcnt(0)
	v_mfma_f32_16x16x32_bf16 v[84:87], v[88:91], v[76:79], v[84:87]
	ds_read_b128 v[88:91], v167 offset:128
	s_waitcnt lgkmcnt(0)
	v_mfma_f32_16x16x32_bf16 v[84:87], v[88:91], v[72:75], v[84:87]
	ds_read_b128 v[88:91], v167 offset:192
	s_waitcnt lgkmcnt(0)
	v_mfma_f32_16x16x32_bf16 v[104:107], v[88:91], v[68:71], v[84:87]
	s_nop 4
	ds_read_b128 v[84:87], v168
	ds_read_b128 v[88:91], v168 offset:64
	s_waitcnt lgkmcnt(1)
	v_mfma_f32_16x16x32_bf16 v[84:87], v[84:87], v[80:83], 0
	s_waitcnt lgkmcnt(0)
	v_mfma_f32_16x16x32_bf16 v[84:87], v[88:91], v[76:79], v[84:87]
	ds_read_b128 v[88:91], v168 offset:128
	s_waitcnt lgkmcnt(0)
	v_mfma_f32_16x16x32_bf16 v[84:87], v[88:91], v[72:75], v[84:87]
	ds_read_b128 v[88:91], v168 offset:192
	s_waitcnt lgkmcnt(0)
	v_mfma_f32_16x16x32_bf16 v[100:103], v[88:91], v[68:71], v[84:87]
	s_nop 4
	ds_read_b128 v[84:87], v169
	ds_read_b128 v[88:91], v169 offset:64
	s_waitcnt lgkmcnt(1)
	v_mfma_f32_16x16x32_bf16 v[84:87], v[84:87], v[80:83], 0
	s_waitcnt lgkmcnt(0)
	v_mfma_f32_16x16x32_bf16 v[84:87], v[88:91], v[76:79], v[84:87]
	ds_read_b128 v[88:91], v169 offset:128
	s_waitcnt lgkmcnt(0)
	v_mfma_f32_16x16x32_bf16 v[84:87], v[88:91], v[72:75], v[84:87]
	ds_read_b128 v[88:91], v169 offset:192
	s_waitcnt lgkmcnt(0)
	v_mfma_f32_16x16x32_bf16 v[96:99], v[88:91], v[68:71], v[84:87]
	s_nop 4
	ds_read_b128 v[84:87], v170
	ds_read_b128 v[88:91], v170 offset:64
	s_waitcnt lgkmcnt(1)
	v_mfma_f32_16x16x32_bf16 v[84:87], v[84:87], v[80:83], 0
	s_waitcnt lgkmcnt(0)
	v_mfma_f32_16x16x32_bf16 v[84:87], v[88:91], v[76:79], v[84:87]
	ds_read_b128 v[88:91], v170 offset:128
	s_waitcnt lgkmcnt(0)
	v_mfma_f32_16x16x32_bf16 v[84:87], v[88:91], v[72:75], v[84:87]
	ds_read_b128 v[88:91], v170 offset:192
	s_waitcnt lgkmcnt(0)
	v_mfma_f32_16x16x32_bf16 v[92:95], v[88:91], v[68:71], v[84:87]
	s_nop 4
	ds_read_b128 v[84:87], v171
	ds_read_b128 v[88:91], v171 offset:64
	s_waitcnt lgkmcnt(1)
	v_mfma_f32_16x16x32_bf16 v[84:87], v[84:87], v[80:83], 0
	s_waitcnt lgkmcnt(0)
	v_mfma_f32_16x16x32_bf16 v[84:87], v[88:91], v[76:79], v[84:87]
	ds_read_b128 v[88:91], v171 offset:128
	s_waitcnt lgkmcnt(0)
	v_mfma_f32_16x16x32_bf16 v[84:87], v[88:91], v[72:75], v[84:87]
	ds_read_b128 v[88:91], v171 offset:192
	s_waitcnt lgkmcnt(0)
	v_mfma_f32_16x16x32_bf16 v[88:91], v[88:91], v[68:71], v[84:87]
	s_nop 4
	ds_read_b128 v[84:87], v172
	s_nop 1
	v_mul_f32_e32 v88, 0x3e0293ee, v88
	s_waitcnt lgkmcnt(0)
	v_mfma_f32_16x16x32_bf16 v[84:87], v[84:87], v[80:83], 0
	v_mfma_f32_16x16x32_bf16 v[84:87], v[180:183], v[76:79], v[84:87]
	ds_read_b128 v[180:183], v172 offset:128
	s_waitcnt lgkmcnt(0)
	v_mfma_f32_16x16x32_bf16 v[84:87], v[180:183], v[72:75], v[84:87]
	ds_read_b128 v[180:183], v172 offset:192
	s_waitcnt lgkmcnt(0)
	v_mfma_f32_16x16x32_bf16 v[84:87], v[180:183], v[68:71], v[84:87]
	ds_read_b128 v[180:183], v173
	s_nop 6
	v_mul_f32_e32 v84, 0x3e0293ee, v84
	s_waitcnt lgkmcnt(0)
	v_mfma_f32_16x16x32_bf16 v[80:83], v[180:183], v[80:83], 0
	ds_read_b128 v[180:183], v173 offset:64
	s_waitcnt lgkmcnt(0)
	v_mfma_f32_16x16x32_bf16 v[76:79], v[180:183], v[76:79], v[80:83]
	s_nop 4
	ds_read_b128 v[80:83], v173 offset:128
	s_waitcnt lgkmcnt(0)
; __device__ void attn_phase(LAS unsigned char* lds, const bf16_t* PROJ, bf16_t* AP, float* LSE) {
;     ...
;         for (int kt = 0; kt < 9; ++kt)
; #pragma unroll
;             for (int j = 0; j < 4; ++j) { const int dd = -64 + 16 * kt + 4 * g + j - fr; const int ki = 128 * b - 64 + 16 * wave + 16 * kt + 4 * g + j;
;                 const bool valid = (dd >= -64) && (dd <= 64) && (ki >= 0) && (ki < L); const float tv = valid ? st[kt][j] * sc : -1e30f; st[kt][j] = tv; mx = fmaxf(mx, tv); }
	v_mfma_f32_16x16x32_bf16 v[72:75], v[80:83], v[72:75], v[76:79]
	v_cndmask_b32_e32 v82, v230, v2, vcc
	v_or_b32_e32 v2, 1, v0
	v_cmp_gt_i32_e32 vcc, s4, v2
	s_and_b64 s[22:23], s[42:43], vcc
	s_and_b64 vcc, s[20:21], s[22:23]
	v_mul_f32_e32 v2, 0x3e0293ee, v113
	v_cndmask_b32_e32 v113, v230, v2, vcc
	v_cmp_gt_i32_e32 vcc, s4, v3
	s_and_b64 s[22:23], s[44:45], vcc
	s_and_b64 vcc, s[20:21], s[22:23]
	v_mul_f32_e32 v3, 0x3e0293ee, v114
	v_or_b32_e32 v0, 3, v0
	v_cndmask_b32_e32 v121, v230, v3, vcc
	v_cmp_gt_i32_e32 vcc, s4, v0
	s_and_b64 s[22:23], s[46:47], vcc
	s_and_b64 vcc, s[20:21], s[22:23]
	v_mul_f32_e32 v0, 0x3e0293ee, v115
	v_max3_f32 v2, v82, s3, v113
	v_cndmask_b32_e32 v114, v230, v0, vcc
	v_max3_f32 v0, v2, v121, v114
	s_cmpk_gt_i32 s2, 0xffef
	v_add_u32_e32 v2, s2, v158
	s_cselect_b64 s[20:21], -1, 0
	v_cmp_gt_i32_e32 vcc, s4, v2
	s_and_b64 vcc, s[20:21], vcc
	v_mul_f32_e32 v3, 0x3e0293ee, v108
	v_cndmask_b32_e32 v123, v230, v3, vcc
	v_or_b32_e32 v3, 1, v2
	v_cmp_gt_i32_e32 vcc, s4, v3
	s_and_b64 vcc, s[20:21], vcc
	v_mul_f32_e32 v3, 0x3e0293ee, v109
	v_cndmask_b32_e32 v112, v230, v3, vcc
	v_or_b32_e32 v3, 2, v2
	v_cmp_gt_i32_e32 vcc, s4, v3
	s_and_b64 vcc, s[20:21], vcc
	v_mul_f32_e32 v3, 0x3e0293ee, v110
	v_or_b32_e32 v2, 3, v2
	v_cndmask_b32_e32 v110, v230, v3, vcc
	v_cmp_gt_i32_e32 vcc, s4, v2
	s_and_b64 vcc, s[20:21], vcc
	v_mul_f32_e32 v2, 0x3e0293ee, v111
	v_cndmask_b32_e32 v108, v230, v2, vcc
	s_cmpk_gt_i32 s2, 0xffdf
	v_add_u32_e32 v2, s2, v159
	s_cselect_b64 s[20:21], -1, 0
	v_cmp_gt_i32_e32 vcc, s4, v2
	s_and_b64 vcc, s[20:21], vcc
	v_mul_f32_e32 v3, 0x3e0293ee, v104
	v_cndmask_b32_e32 v111, v230, v3, vcc
	v_or_b32_e32 v3, 1, v2
	v_cmp_gt_i32_e32 vcc, s4, v3
	s_and_b64 vcc, s[20:21], vcc
	v_mul_f32_e32 v3, 0x3e0293ee, v105
	v_cndmask_b32_e32 v83, v230, v3, vcc
	v_or_b32_e32 v3, 2, v2
	v_cmp_gt_i32_e32 vcc, s4, v3
	ds_read_b128 v[76:79], v173 offset:192
	s_and_b64 vcc, s[20:21], vcc
	v_mul_f32_e32 v3, 0x3e0293ee, v106
	v_or_b32_e32 v2, 3, v2
	v_cndmask_b32_e32 v109, v230, v3, vcc
	v_cmp_gt_i32_e32 vcc, s4, v2
	s_and_b64 vcc, s[20:21], vcc
	v_mul_f32_e32 v2, 0x3e0293ee, v107
	v_cndmask_b32_e32 v81, v230, v2, vcc
	s_cmpk_gt_i32 s2, 0xffcf
	v_add_u32_e32 v2, s2, v160
	s_cselect_b64 s[20:21], -1, 0
	v_cmp_gt_i32_e32 vcc, s4, v2
	s_and_b64 vcc, s[20:21], vcc
	v_mul_f32_e32 v3, 0x3e0293ee, v100
	v_cndmask_b32_e32 v80, v230, v3, vcc
	v_or_b32_e32 v3, 1, v2
	v_cmp_gt_i32_e32 vcc, s4, v3
	s_and_b64 vcc, s[20:21], vcc
	v_mul_f32_e32 v3, 0x3e0293ee, v101
	s_waitcnt lgkmcnt(0)
	v_mfma_f32_16x16x32_bf16 v[68:71], v[76:79], v[68:71], v[72:75]
	v_cndmask_b32_e32 v78, v230, v3, vcc
	v_or_b32_e32 v3, 2, v2
	v_cmp_gt_i32_e32 vcc, s4, v3
	s_and_b64 vcc, s[20:21], vcc
	v_mul_f32_e32 v3, 0x3e0293ee, v102
	v_or_b32_e32 v2, 3, v2
	v_cndmask_b32_e32 v76, v230, v3, vcc
	v_cmp_gt_i32_e32 vcc, s4, v2
	s_and_b64 vcc, s[20:21], vcc
	v_mul_f32_e32 v2, 0x3e0293ee, v103
	s_cmp_gt_i32 s14, -1
	v_or_b32_e32 v74, s14, v133
	v_cndmask_b32_e32 v73, v230, v2, vcc
	s_cselect_b64 s[20:21], -1, 0
	v_cmp_gt_i32_e32 vcc, s4, v74
	s_and_b64 vcc, s[20:21], vcc
	v_mul_f32_e32 v2, 0x3e0293ee, v96
	v_cndmask_b32_e32 v72, v230, v2, vcc
	v_or_b32_e32 v2, 1, v74
	v_cmp_gt_i32_e32 vcc, s4, v2
	s_and_b64 vcc, s[20:21], vcc
	v_mul_f32_e32 v2, 0x3e0293ee, v97
	v_or_b32_e32 v3, 2, v74
	v_cndmask_b32_e32 v2, v230, v2, vcc
	v_cmp_gt_i32_e32 vcc, s4, v3
	s_and_b64 vcc, s[20:21], vcc
	v_mul_f32_e32 v3, 0x3e0293ee, v98
	v_or_b32_e32 v74, 3, v74
	v_cndmask_b32_e32 v3, v230, v3, vcc
	v_cmp_gt_i32_e32 vcc, s4, v74
	s_and_b64 vcc, s[20:21], vcc
	v_mul_f32_e32 v74, 0x3e0293ee, v99
	s_cmpk_gt_i32 s2, 0xffaf
	v_add_u32_e32 v96, s2, v161
	v_cndmask_b32_e32 v74, v230, v74, vcc
	s_cselect_b64 s[20:21], -1, 0
	v_cmp_gt_i32_e32 vcc, s4, v96
	s_and_b64 vcc, s[20:21], vcc
	v_mul_f32_e32 v75, 0x3e0293ee, v92
	v_or_b32_e32 v77, 1, v96
	v_cndmask_b32_e32 v75, v230, v75, vcc
	v_cmp_gt_i32_e32 vcc, s4, v77
	s_and_b64 vcc, s[20:21], vcc
	v_mul_f32_e32 v77, 0x3e0293ee, v93
	v_or_b32_e32 v79, 2, v96
	v_cndmask_b32_e32 v77, v230, v77, vcc
	v_cmp_gt_i32_e32 vcc, s4, v79
	s_and_b64 vcc, s[20:21], vcc
	v_mul_f32_e32 v79, 0x3e0293ee, v94
	v_or_b32_e32 v92, 3, v96
	v_cndmask_b32_e32 v79, v230, v79, vcc
	v_cmp_gt_i32_e32 vcc, s4, v92
	s_and_b64 vcc, s[20:21], vcc
	v_mul_f32_e32 v92, 0x3e0293ee, v95
	v_cndmask_b32_e32 v104, v230, v92, vcc
	s_cmpk_gt_i32 s2, 0xff9f
	v_add_u32_e32 v92, s2, v162
	s_cselect_b64 s[20:21], -1, 0
	v_cmp_gt_i32_e32 vcc, s4, v92
	s_and_b64 vcc, s[20:21], vcc
	v_max3_f32 v0, v0, v123, v112
	v_cndmask_b32_e32 v105, v230, v88, vcc
	v_or_b32_e32 v88, 1, v92
	v_cmp_gt_i32_e32 vcc, s4, v88
	s_and_b64 vcc, s[20:21], vcc
	v_mul_f32_e32 v88, 0x3e0293ee, v89
	v_cndmask_b32_e32 v106, v230, v88, vcc
	v_or_b32_e32 v88, 2, v92
	v_cmp_gt_i32_e32 vcc, s4, v88
	s_and_b64 vcc, s[20:21], vcc
	v_mul_f32_e32 v88, 0x3e0293ee, v90
	v_cndmask_b32_e32 v107, v230, v88, vcc
	v_or_b32_e32 v88, 3, v92
	v_cmp_gt_i32_e32 vcc, s4, v88
	s_and_b64 vcc, s[20:21], vcc
	v_mul_f32_e32 v88, 0x3e0293ee, v91
	v_cndmask_b32_e32 v115, v230, v88, vcc
	s_cmpk_gt_i32 s2, 0xff8f
	v_add_u32_e32 v88, s2, v163
	s_cselect_b64 s[20:21], -1, 0
	v_cmp_gt_i32_e32 vcc, s4, v88
	s_and_b64 vcc, s[20:21], vcc
	v_max3_f32 v0, v0, v110, v108
	v_cndmask_b32_e32 v125, v230, v84, vcc
	v_or_b32_e32 v84, 1, v88
	v_cmp_gt_i32_e32 vcc, s4, v84
	s_and_b64 vcc, s[20:21], vcc
	v_mul_f32_e32 v84, 0x3e0293ee, v85
	v_cndmask_b32_e32 v127, v230, v84, vcc
	v_or_b32_e32 v84, 2, v88
	v_cmp_gt_i32_e32 vcc, s4, v84
	s_and_b64 vcc, s[20:21], vcc
	v_mul_f32_e32 v84, 0x3e0293ee, v86
	v_cndmask_b32_e32 v180, v230, v84, vcc
	v_or_b32_e32 v84, 3, v88
; #define LAS __attribute__((address_space(3)))
; #define MFMA16(a, b, c) __builtin_amdgcn_mfma_f32_16x16x32_bf16((a), (b), (c), 0, 0, 0)
; __device__ void attn_phase(LAS unsigned char* lds, const bf16_t* PROJ, bf16_t* AP, float* LSE) {
;     ...
;             for (int j = 0; j < 4; ++j) { const int dd = -64 + 16 * kt + 4 * g + j - fr; const int ki = 128 * b - 64 + 16 * wave + 16 * kt + 4 * g + j;
;                 const bool valid = (dd >= -64) && (dd <= 64) && (ki >= 0) && (ki < L); const float tv = valid ? st[kt][j] * sc : -1e30f; st[kt][j] = tv; mx = fmaxf(mx, tv); }
;         mx = fmaxf(mx, __shfl_xor(mx, 16)); mx = fmaxf(mx, __shfl_xor(mx, 32));
;         float den = 0.f;
; #pragma unroll
;         for (int kt = 0; kt < 9; ++kt)
; #pragma unroll
;             for (int j = 0; j < 4; ++j) { const float pr = st[kt][j] > -1e29f ? __builtin_amdgcn_exp2f(st[kt][j] - mx) : 0.f; st[kt][j] = pr; den += pr; }
;         den += __shfl_xor(den, 16); den += __shfl_xor(den, 32);
;         f32x4 o[8];
; #pragma unroll
;         for (int c = 0; c < 8; ++c) o[c] = (f32x4){0.f, 0.f, 0.f, 0.f};
; #pragma unroll
;         for (int kk = 0; kk < 5; ++kk) {
;             const bf16x8 pa = pack8(st[2 * kk], (2 * kk + 1 < 9) ? st[(2 * kk + 1 < 9) ? 2 * kk + 1 : 8] : (f32x4){0.f, 0.f, 0.f, 0.f});
;             LAS unsigned char* vb = Vl + (16 * wave + 32 * kk + 4 * g + q4) * KP + 8 * p4;
; #pragma unroll
;             for (int c = 0; c < 8; ++c) { const bf16x8 bfrag = tr_pair(vb + 32 * c, vb + 16 * KP + 32 * c); o[c] = MFMA16(pa, bfrag, o[c]); }
	v_max3_f32 v0, v0, v111, v83
	v_cmp_gt_i32_e32 vcc, s4, v84
	v_max3_f32 v0, v0, v109, v81
	s_and_b64 vcc, s[20:21], vcc
	v_mul_f32_e32 v84, 0x3e0293ee, v87
	v_max3_f32 v0, v0, v80, v78
	v_cndmask_b32_e32 v181, v230, v84, vcc
	v_add_u32_e32 v84, s2, v164
	v_max3_f32 v0, v0, v76, v73
	s_cmpk_gt_i32 s2, 0xff7f
	v_cmp_gt_i32_e32 vcc, s4, v84
	v_max3_f32 v0, v0, v72, v2
	s_cselect_b64 s[20:21], -1, 0
	s_and_b64 s[2:3], s[48:49], vcc
	v_max3_f32 v0, v0, v3, v74
	s_and_b64 vcc, s[20:21], s[2:3]
	v_mul_f32_e32 v68, 0x3e0293ee, v68
	v_or_b32_e32 v85, 1, v84
	v_max3_f32 v0, v0, v75, v77
	v_cndmask_b32_e32 v68, v230, v68, vcc
	s_and_b64 s[2:3], s[50:51], s[20:21]
	v_cmp_gt_i32_e32 vcc, s4, v85
	v_max3_f32 v0, v0, v79, v104
	s_and_b64 vcc, s[2:3], vcc
	v_mul_f32_e32 v69, 0x3e0293ee, v69
	v_or_b32_e32 v85, 2, v84
	v_max3_f32 v0, v0, v105, v106
	v_cndmask_b32_e32 v69, v230, v69, vcc
	s_and_b64 s[2:3], s[52:53], s[20:21]
	v_cmp_gt_i32_e32 vcc, s4, v85
	v_max3_f32 v0, v0, v107, v115
	s_and_b64 vcc, s[2:3], vcc
	v_mul_f32_e32 v70, 0x3e0293ee, v70
	v_or_b32_e32 v84, 3, v84
	v_max3_f32 v0, v0, v125, v127
	v_cndmask_b32_e32 v70, v230, v70, vcc
	s_and_b64 s[2:3], s[54:55], s[20:21]
	v_cmp_gt_i32_e32 vcc, s4, v84
	v_max3_f32 v0, v0, v180, v181
	s_and_b64 vcc, s[2:3], vcc
	v_mul_f32_e32 v71, 0x3e0293ee, v71
	v_max3_f32 v0, v0, v68, v69
	v_cndmask_b32_e32 v71, v230, v71, vcc
	v_max3_f32 v0, v0, v70, v71
	ds_bpermute_b32 v84, v134, v0
	v_cmp_lt_f32_e32 vcc, s11, v82
	s_mul_hi_i32 s3, s16, 0x6000
	s_mul_i32 s2, s16, 0x6000
	s_waitcnt lgkmcnt(0)
	v_max_f32_e32 v84, v84, v84
	v_max_f32_e32 v0, v0, v84
	ds_bpermute_b32 v84, v135, v0
	s_waitcnt lgkmcnt(0)
	v_max_f32_e32 v84, v84, v84
	v_max_f32_e32 v0, v0, v84
	v_sub_f32_e32 v82, v82, v0
	v_exp_f32_e32 v82, v82
	v_sub_f32_e32 v84, v113, v0
	v_exp_f32_e32 v84, v84
	v_cndmask_b32_e32 v91, 0, v82, vcc
	v_cmp_lt_f32_e32 vcc, s11, v113
	v_add_f32_e32 v82, 0, v91
	s_nop 0
	v_cndmask_b32_e32 v93, 0, v84, vcc
	v_sub_f32_e32 v84, v121, v0
	v_exp_f32_e32 v84, v84
	v_cmp_lt_f32_e32 vcc, s11, v121
	v_add_f32_e32 v82, v93, v82
	s_nop 0
	v_cndmask_b32_e32 v95, 0, v84, vcc
	v_sub_f32_e32 v84, v114, v0
	v_exp_f32_e32 v84, v84
	v_cmp_lt_f32_e32 vcc, s11, v114
	v_add_f32_e32 v82, v95, v82
	s_nop 0
	v_cndmask_b32_e32 v97, 0, v84, vcc
	v_sub_f32_e32 v84, v123, v0
	v_exp_f32_e32 v84, v84
	v_cmp_lt_f32_e32 vcc, s11, v123
	v_add_f32_e32 v82, v97, v82
	s_nop 0
	v_cndmask_b32_e32 v99, 0, v84, vcc
	v_sub_f32_e32 v84, v112, v0
	v_exp_f32_e32 v84, v84
	v_cmp_lt_f32_e32 vcc, s11, v112
	v_add_f32_e32 v82, v99, v82
	s_nop 0
	v_cndmask_b32_e32 v101, 0, v84, vcc
	v_sub_f32_e32 v84, v110, v0
	v_exp_f32_e32 v84, v84
	v_cmp_lt_f32_e32 vcc, s11, v110
	v_add_f32_e32 v82, v101, v82
	s_nop 0
	v_cndmask_b32_e32 v102, 0, v84, vcc
	v_sub_f32_e32 v84, v108, v0
	v_exp_f32_e32 v84, v84
	v_cmp_lt_f32_e32 vcc, s11, v108
	v_add_f32_e32 v82, v102, v82
	s_nop 0
	v_cndmask_b32_e32 v103, 0, v84, vcc
	v_sub_f32_e32 v84, v111, v0
	v_exp_f32_e32 v84, v84
	v_cmp_lt_f32_e32 vcc, s11, v111
	v_add_f32_e32 v82, v103, v82
	s_nop 0
	v_cndmask_b32_e32 v88, 0, v84, vcc
	v_cmp_lt_f32_e32 vcc, s11, v83
	v_sub_f32_e32 v83, v83, v0
	v_exp_f32_e32 v83, v83
	v_add_f32_e32 v82, v88, v82
	v_cndmask_b32_e32 v89, 0, v83, vcc
	v_sub_f32_e32 v83, v109, v0
	v_exp_f32_e32 v83, v83
	v_cmp_lt_f32_e32 vcc, s11, v109
	v_add_f32_e32 v82, v89, v82
	ds_read_b64_tr_b16 v[110:111], v153 offset:4352
	ds_read_b64_tr_b16 v[108:109], v153
	ds_read_b64_tr_b16 v[112:113], v153 offset:32
	v_cndmask_b32_e32 v90, 0, v83, vcc
	v_cmp_lt_f32_e32 vcc, s11, v81
	v_sub_f32_e32 v81, v81, v0
	v_exp_f32_e32 v81, v81
	v_add_f32_e32 v82, v90, v82
	v_cvt_pk_bf16_f32 v88, v88, v89
	v_cndmask_b32_e32 v92, 0, v81, vcc
	v_cmp_lt_f32_e32 vcc, s11, v80
	v_sub_f32_e32 v80, v80, v0
	v_exp_f32_e32 v80, v80
	v_add_f32_e32 v81, v92, v82
	v_cvt_pk_bf16_f32 v89, v90, v92
	v_cndmask_b32_e32 v94, 0, v80, vcc
	v_cmp_lt_f32_e32 vcc, s11, v78
	v_sub_f32_e32 v78, v78, v0
	v_exp_f32_e32 v78, v78
	v_add_f32_e32 v80, v94, v81
	v_cndmask_b32_e32 v96, 0, v78, vcc
	v_cmp_lt_f32_e32 vcc, s11, v76
	v_sub_f32_e32 v76, v76, v0
	v_exp_f32_e32 v76, v76
	v_add_f32_e32 v78, v96, v80
	v_cvt_pk_bf16_f32 v90, v94, v96
	v_cndmask_b32_e32 v98, 0, v76, vcc
	v_cmp_lt_f32_e32 vcc, s11, v73
	v_sub_f32_e32 v73, v73, v0
	v_exp_f32_e32 v73, v73
	v_add_f32_e32 v76, v98, v78
	v_cndmask_b32_e32 v100, 0, v73, vcc
	v_cmp_lt_f32_e32 vcc, s11, v72
	v_sub_f32_e32 v72, v72, v0
	v_exp_f32_e32 v72, v72
	v_add_f32_e32 v73, v100, v76
	v_cndmask_b32_e32 v80, 0, v72, vcc
	v_cmp_lt_f32_e32 vcc, s11, v2
	v_sub_f32_e32 v2, v2, v0
	v_exp_f32_e32 v2, v2
	v_add_f32_e32 v72, v80, v73
	v_cndmask_b32_e32 v81, 0, v2, vcc
	v_cmp_lt_f32_e32 vcc, s11, v3
	v_sub_f32_e32 v3, v3, v0
	v_exp_f32_e32 v3, v3
	v_add_f32_e32 v2, v81, v72
	v_cvt_pk_bf16_f32 v80, v80, v81
	v_cndmask_b32_e32 v82, 0, v3, vcc
	v_sub_f32_e32 v3, v74, v0
	v_exp_f32_e32 v3, v3
	v_cmp_lt_f32_e32 vcc, s11, v74
	v_add_f32_e32 v2, v82, v2
	s_nop 0
	v_cndmask_b32_e32 v83, 0, v3, vcc
	v_sub_f32_e32 v3, v75, v0
	v_exp_f32_e32 v3, v3
	v_cmp_lt_f32_e32 vcc, s11, v75
	v_add_f32_e32 v2, v83, v2
	v_cvt_pk_bf16_f32 v81, v82, v83
	v_cndmask_b32_e32 v84, 0, v3, vcc
	v_sub_f32_e32 v3, v77, v0
	v_exp_f32_e32 v3, v3
	v_cmp_lt_f32_e32 vcc, s11, v77
	v_add_f32_e32 v2, v84, v2
	s_nop 0
	v_cndmask_b32_e32 v85, 0, v3, vcc
	v_sub_f32_e32 v3, v79, v0
	v_exp_f32_e32 v3, v3
	v_cmp_lt_f32_e32 vcc, s11, v79
	v_add_f32_e32 v2, v85, v2
	v_cvt_pk_bf16_f32 v82, v84, v85
	v_cndmask_b32_e32 v86, 0, v3, vcc
	v_sub_f32_e32 v3, v104, v0
	v_exp_f32_e32 v3, v3
	v_cmp_lt_f32_e32 vcc, s11, v104
	v_cvt_pk_bf16_f32 v104, v91, v93
	v_cvt_pk_bf16_f32 v91, v98, v100
	v_cndmask_b32_e32 v87, 0, v3, vcc
	v_sub_f32_e32 v3, v105, v0
	v_exp_f32_e32 v3, v3
	v_cmp_lt_f32_e32 vcc, s11, v105
	v_cvt_pk_bf16_f32 v105, v95, v97
	v_add_f32_e32 v2, v86, v2
	v_cndmask_b32_e32 v72, 0, v3, vcc
	v_sub_f32_e32 v3, v106, v0
	v_exp_f32_e32 v3, v3
	v_cmp_lt_f32_e32 vcc, s11, v106
	v_cvt_pk_bf16_f32 v106, v99, v101
	v_add_f32_e32 v2, v87, v2
	v_cndmask_b32_e32 v73, 0, v3, vcc
	v_sub_f32_e32 v3, v107, v0
	v_exp_f32_e32 v3, v3
	v_cmp_lt_f32_e32 vcc, s11, v107
	v_cvt_pk_bf16_f32 v107, v102, v103
	v_cvt_pk_bf16_f32 v83, v86, v87
	v_cndmask_b32_e32 v74, 0, v3, vcc
	v_sub_f32_e32 v3, v115, v0
	v_exp_f32_e32 v3, v3
	v_cmp_lt_f32_e32 vcc, s11, v115
	ds_read_b64_tr_b16 v[114:115], v153 offset:4384
	s_waitcnt lgkmcnt(2)
; #define LAS __attribute__((address_space(3)))
; #define MFMA16(a, b, c) __builtin_amdgcn_mfma_f32_16x16x32_bf16((a), (b), (c), 0, 0, 0)
; __device__ void attn_phase(LAS unsigned char* lds, const bf16_t* PROJ, bf16_t* AP, float* LSE) {
;     ...
;             for (int j = 0; j < 4; ++j) { const float pr = st[kt][j] > -1e29f ? __builtin_amdgcn_exp2f(st[kt][j] - mx) : 0.f; st[kt][j] = pr; den += pr; }
;         den += __shfl_xor(den, 16); den += __shfl_xor(den, 32);
;         f32x4 o[8];
; #pragma unroll
;         for (int c = 0; c < 8; ++c) o[c] = (f32x4){0.f, 0.f, 0.f, 0.f};
; #pragma unroll
;         for (int kk = 0; kk < 5; ++kk) {
;             const bf16x8 pa = pack8(st[2 * kk], (2 * kk + 1 < 9) ? st[(2 * kk + 1 < 9) ? 2 * kk + 1 : 8] : (f32x4){0.f, 0.f, 0.f, 0.f});
;             LAS unsigned char* vb = Vl + (16 * wave + 32 * kk + 4 * g + q4) * KP + 8 * p4;
; #pragma unroll
;             for (int c = 0; c < 8; ++c) { const bf16x8 bfrag = tr_pair(vb + 32 * c, vb + 16 * KP + 32 * c); o[c] = MFMA16(pa, bfrag, o[c]); }
;         }
	v_mfma_f32_16x16x32_bf16 v[108:111], v[104:107], v[108:111], 0
	v_cndmask_b32_e32 v75, 0, v3, vcc
	v_sub_f32_e32 v3, v125, v0
	v_exp_f32_e32 v3, v3
	v_cmp_lt_f32_e32 vcc, s11, v125
	s_waitcnt lgkmcnt(0)
	v_mfma_f32_16x16x32_bf16 v[112:115], v[104:107], v[112:115], 0
	v_add_f32_e32 v2, v72, v2
	v_cndmask_b32_e32 v76, 0, v3, vcc
	v_sub_f32_e32 v3, v127, v0
	v_exp_f32_e32 v3, v3
	v_cmp_lt_f32_e32 vcc, s11, v127
	v_add_f32_e32 v2, v73, v2
	v_add_f32_e32 v2, v74, v2
	v_cndmask_b32_e32 v77, 0, v3, vcc
	v_sub_f32_e32 v3, v180, v0
	v_exp_f32_e32 v3, v3
	v_cmp_lt_f32_e32 vcc, s11, v180
	v_add_f32_e32 v2, v75, v2
	v_add_f32_e32 v2, v76, v2
	v_cndmask_b32_e32 v78, 0, v3, vcc
	v_cmp_lt_f32_e32 vcc, s11, v181
	v_sub_f32_e32 v3, v181, v0
	ds_read_b64_tr_b16 v[180:181], v153 offset:64
	ds_read_b64_tr_b16 v[182:183], v153 offset:4416
	ds_read_b64_tr_b16 v[184:185], v153 offset:96
	ds_read_b64_tr_b16 v[186:187], v153 offset:4448
	ds_read_b64_tr_b16 v[188:189], v153 offset:128
	ds_read_b64_tr_b16 v[190:191], v153 offset:4480
	ds_read_b64_tr_b16 v[192:193], v153 offset:160
	ds_read_b64_tr_b16 v[194:195], v153 offset:4512
	ds_read_b64_tr_b16 v[196:197], v153 offset:192
	ds_read_b64_tr_b16 v[198:199], v153 offset:4544
	ds_read_b64_tr_b16 v[200:201], v153 offset:224
	ds_read_b64_tr_b16 v[202:203], v153 offset:4576
	ds_read_b64_tr_b16 v[92:93], v153 offset:8704
	ds_read_b64_tr_b16 v[94:95], v153 offset:13056
	ds_read_b64_tr_b16 v[96:97], v153 offset:8736
	ds_read_b64_tr_b16 v[98:99], v153 offset:13088
	s_waitcnt lgkmcnt(14)
	v_mfma_f32_16x16x32_bf16 v[180:183], v[104:107], v[180:183], 0
	v_exp_f32_e32 v3, v3
	v_add_f32_e32 v2, v77, v2
	v_add_f32_e32 v2, v78, v2
	s_waitcnt lgkmcnt(12)
	v_mfma_f32_16x16x32_bf16 v[184:187], v[104:107], v[184:187], 0
	v_cndmask_b32_e32 v79, 0, v3, vcc
	v_add_f32_e32 v2, v79, v2
	v_cvt_pk_bf16_f32 v72, v72, v73
	s_waitcnt lgkmcnt(10)
	v_mfma_f32_16x16x32_bf16 v[188:191], v[104:107], v[188:191], 0
	v_cvt_pk_bf16_f32 v73, v74, v75
	v_cvt_pk_bf16_f32 v74, v76, v77
	v_cvt_pk_bf16_f32 v75, v78, v79
	s_waitcnt lgkmcnt(8)
	v_mfma_f32_16x16x32_bf16 v[192:195], v[104:107], v[192:195], 0
	v_sub_f32_e32 v3, v68, v0
	v_exp_f32_e32 v3, v3
	v_cmp_lt_f32_e32 vcc, s11, v68
	s_waitcnt lgkmcnt(6)
	v_mfma_f32_16x16x32_bf16 v[196:199], v[104:107], v[196:199], 0
	v_cndmask_b32_e32 v68, 0, v3, vcc
	v_sub_f32_e32 v3, v69, v0
	s_waitcnt lgkmcnt(4)
	v_mfma_f32_16x16x32_bf16 v[102:105], v[104:107], v[200:203], 0
	v_exp_f32_e32 v3, v3
	v_cmp_lt_f32_e32 vcc, s11, v69
	v_add_f32_e32 v2, v68, v2
	s_waitcnt lgkmcnt(2)
	v_mfma_f32_16x16x32_bf16 v[92:95], v[88:91], v[92:95], v[108:111]
	ds_read_b64_tr_b16 v[106:107], v153 offset:8768
	s_nop 1
	ds_read_b64_tr_b16 v[108:109], v153 offset:13120
	v_cndmask_b32_e32 v69, 0, v3, vcc
	v_sub_f32_e32 v3, v70, v0
	s_waitcnt lgkmcnt(2)
	v_mfma_f32_16x16x32_bf16 v[96:99], v[88:91], v[96:99], v[112:115]
	ds_read_b64_tr_b16 v[110:111], v153 offset:8800
	s_nop 1
	ds_read_b64_tr_b16 v[112:113], v153 offset:13152
	v_exp_f32_e32 v3, v3
	v_cmp_lt_f32_e32 vcc, s11, v70
	s_waitcnt lgkmcnt(2)
	v_mfma_f32_16x16x32_bf16 v[106:109], v[88:91], v[106:109], v[180:183]
	s_nop 2
	ds_read_b64_tr_b16 v[180:181], v153 offset:8832
	ds_read_b64_tr_b16 v[182:183], v153 offset:13184
	v_cndmask_b32_e32 v70, 0, v3, vcc
	v_sub_f32_e32 v3, v71, v0
	s_waitcnt lgkmcnt(2)
	v_mfma_f32_16x16x32_bf16 v[110:113], v[88:91], v[110:113], v[184:187]
	s_nop 2
	ds_read_b64_tr_b16 v[184:185], v153 offset:8864
	ds_read_b64_tr_b16 v[186:187], v153 offset:13216
	v_exp_f32_e32 v3, v3
	v_add_f32_e32 v2, v69, v2
	s_waitcnt lgkmcnt(2)
	v_mfma_f32_16x16x32_bf16 v[180:183], v[88:91], v[180:183], v[188:191]
	s_nop 2
	ds_read_b64_tr_b16 v[188:189], v153 offset:8896
	ds_read_b64_tr_b16 v[190:191], v153 offset:13248
	v_cmp_lt_f32_e32 vcc, s11, v71
	v_add_f32_e32 v2, v70, v2
	s_waitcnt lgkmcnt(2)
	v_mfma_f32_16x16x32_bf16 v[184:187], v[88:91], v[184:187], v[192:195]
	s_nop 2
	ds_read_b64_tr_b16 v[192:193], v153 offset:8928
	ds_read_b64_tr_b16 v[194:195], v153 offset:13280
	ds_read_b64_tr_b16 v[84:85], v153 offset:17408
	ds_read_b64_tr_b16 v[86:87], v153 offset:21760
	v_cndmask_b32_e32 v71, 0, v3, vcc
	s_waitcnt lgkmcnt(0)
	v_mfma_f32_16x16x32_bf16 v[84:87], v[80:83], v[84:87], v[92:95]
	s_nop 2
	ds_read_b64_tr_b16 v[92:93], v153 offset:17440
	ds_read_b64_tr_b16 v[94:95], v153 offset:21792
	v_add_f32_e32 v2, v71, v2
	ds_bpermute_b32 v3, v134, v2
	s_waitcnt lgkmcnt(1)
	v_mfma_f32_16x16x32_bf16 v[92:95], v[80:83], v[92:95], v[96:99]
	s_nop 2
	ds_read_b64_tr_b16 v[96:97], v153 offset:17472
	ds_read_b64_tr_b16 v[98:99], v153 offset:21824
	s_waitcnt lgkmcnt(2)
	v_add_f32_e32 v2, v2, v3
	ds_bpermute_b32 v3, v135, v2
	v_mfma_f32_16x16x32_bf16 v[188:191], v[88:91], v[188:191], v[196:199]
	v_mfma_f32_16x16x32_bf16 v[88:91], v[88:91], v[192:195], v[102:105]
	ds_read_b64_tr_b16 v[100:101], v153 offset:17504
	s_nop 1
	ds_read_b64_tr_b16 v[102:103], v153 offset:21856
	s_waitcnt lgkmcnt(3)
; #define LAS __attribute__((address_space(3)))
; #define MFMA16(a, b, c) __builtin_amdgcn_mfma_f32_16x16x32_bf16((a), (b), (c), 0, 0, 0)
; __device__ void attn_phase(LAS unsigned char* lds, const bf16_t* PROJ, bf16_t* AP, float* LSE) {
;     ...
; #pragma unroll
;         for (int kk = 0; kk < 5; ++kk) {
;             const bf16x8 pa = pack8(st[2 * kk], (2 * kk + 1 < 9) ? st[(2 * kk + 1 < 9) ? 2 * kk + 1 : 8] : (f32x4){0.f, 0.f, 0.f, 0.f});
;             LAS unsigned char* vb = Vl + (16 * wave + 32 * kk + 4 * g + q4) * KP + 8 * p4;
; #pragma unroll
;             for (int c = 0; c < 8; ++c) { const bf16x8 bfrag = tr_pair(vb + 32 * c, vb + 16 * KP + 32 * c); o[c] = MFMA16(pa, bfrag, o[c]); }
;         }
;         const float rden = 1.0f / den;
;         if (g == 0) LSE[((size_t)pat * T + qtok) * 8 + h] = (mx + __log2f(den)) * 0.6931471805599453f;
	v_mfma_f32_16x16x32_bf16 v[96:99], v[80:83], v[96:99], v[106:109]
	ds_read_b64_tr_b16 v[104:105], v153 offset:17536
	s_nop 1
	ds_read_b64_tr_b16 v[106:107], v153 offset:21888
	s_waitcnt lgkmcnt(2)
	v_mfma_f32_16x16x32_bf16 v[100:103], v[80:83], v[100:103], v[110:113]
	ds_read_b64_tr_b16 v[108:109], v153 offset:17568
	s_nop 1
	ds_read_b64_tr_b16 v[110:111], v153 offset:21920
	ds_read_b64_tr_b16 v[112:113], v153 offset:17600
	ds_read_b64_tr_b16 v[114:115], v153 offset:21952
	s_waitcnt lgkmcnt(4)
	v_mfma_f32_16x16x32_bf16 v[104:107], v[80:83], v[104:107], v[180:183]
	s_nop 2
	ds_read_b64_tr_b16 v[180:181], v153 offset:17632
	ds_read_b64_tr_b16 v[182:183], v153 offset:21984
	ds_read_b64_tr_b16 v[76:77], v153 offset:26112
	ds_read_b64_tr_b16 v[78:79], v153 offset:30464
	s_waitcnt lgkmcnt(0)
	v_mfma_f32_16x16x32_bf16 v[76:79], v[72:75], v[76:79], v[84:87]
	s_nop 2
	ds_read_b64_tr_b16 v[84:85], v153 offset:26144
	ds_read_b64_tr_b16 v[86:87], v153 offset:30496
	v_mfma_f32_16x16x32_bf16 v[108:111], v[80:83], v[108:111], v[184:187]
	v_mfma_f32_16x16x32_bf16 v[112:115], v[80:83], v[112:115], v[188:191]
	v_mfma_f32_16x16x32_bf16 v[80:83], v[80:83], v[180:183], v[88:91]
	s_nop 2
	ds_read_b64_tr_b16 v[88:89], v153 offset:26176
	ds_read_b64_tr_b16 v[90:91], v153 offset:30528
	s_waitcnt lgkmcnt(2)
	v_mfma_f32_16x16x32_bf16 v[84:87], v[72:75], v[84:87], v[92:95]
	s_nop 2
	ds_read_b64_tr_b16 v[92:93], v153 offset:26208
	ds_read_b64_tr_b16 v[94:95], v153 offset:30560
	s_waitcnt lgkmcnt(2)
	v_mfma_f32_16x16x32_bf16 v[88:91], v[72:75], v[88:91], v[96:99]
	s_nop 2
	ds_read_b64_tr_b16 v[96:97], v153 offset:26240
	ds_read_b64_tr_b16 v[98:99], v153 offset:30592
	s_waitcnt lgkmcnt(2)
	v_mfma_f32_16x16x32_bf16 v[92:95], v[72:75], v[92:95], v[100:103]
	s_nop 2
	ds_read_b64_tr_b16 v[100:101], v153 offset:26272
	ds_read_b64_tr_b16 v[102:103], v153 offset:30624
	s_waitcnt lgkmcnt(2)
	v_mfma_f32_16x16x32_bf16 v[96:99], v[72:75], v[96:99], v[104:107]
	s_nop 2
	ds_read_b64_tr_b16 v[104:105], v153 offset:26304
	ds_read_b64_tr_b16 v[106:107], v153 offset:30656
	s_waitcnt lgkmcnt(2)
	v_mfma_f32_16x16x32_bf16 v[100:103], v[72:75], v[100:103], v[108:111]
	s_nop 2
	ds_read_b64_tr_b16 v[108:109], v153 offset:26336
	ds_read_b64_tr_b16 v[110:111], v153 offset:30688
	s_waitcnt lgkmcnt(2)
	v_mfma_f32_16x16x32_bf16 v[104:107], v[72:75], v[104:107], v[112:115]
	s_waitcnt lgkmcnt(0)
	v_mfma_f32_16x16x32_bf16 v[108:111], v[72:75], v[108:111], v[80:83]
	s_nop 0
	v_cvt_pk_bf16_f32 v112, v68, v69
	v_cvt_pk_bf16_f32 v113, v70, v71
	v_mov_b32_e32 v114, v1
	v_mov_b32_e32 v115, v1
	ds_read_b64_tr_b16 v[68:69], v153 offset:34816
	ds_read_b64_tr_b16 v[70:71], v153 offset:39168
	ds_read_b64_tr_b16 v[72:73], v153 offset:34848
	ds_read_b64_tr_b16 v[74:75], v153 offset:39200
	s_waitcnt lgkmcnt(2)
	v_mfma_f32_16x16x32_bf16 v[68:71], v[112:115], v[68:71], v[76:79]
	s_nop 2
	ds_read_b64_tr_b16 v[76:77], v153 offset:34880
	ds_read_b64_tr_b16 v[78:79], v153 offset:39232
	ds_read_b64_tr_b16 v[80:81], v153 offset:34912
	ds_read_b64_tr_b16 v[82:83], v153 offset:39264
	s_waitcnt lgkmcnt(4)
	v_mfma_f32_16x16x32_bf16 v[72:75], v[112:115], v[72:75], v[84:87]
	s_nop 2
	ds_read_b64_tr_b16 v[84:85], v153 offset:34944
	ds_read_b64_tr_b16 v[86:87], v153 offset:39296
	s_waitcnt lgkmcnt(4)
	v_mfma_f32_16x16x32_bf16 v[76:79], v[112:115], v[76:79], v[88:91]
	s_nop 2
	ds_read_b64_tr_b16 v[88:89], v153 offset:34976
	ds_read_b64_tr_b16 v[90:91], v153 offset:39328
	s_waitcnt lgkmcnt(4)
	v_mfma_f32_16x16x32_bf16 v[80:83], v[112:115], v[80:83], v[92:95]
	s_nop 2
	ds_read_b64_tr_b16 v[92:93], v153 offset:35008
	ds_read_b64_tr_b16 v[94:95], v153 offset:39360
	s_waitcnt lgkmcnt(4)
	v_mfma_f32_16x16x32_bf16 v[84:87], v[112:115], v[84:87], v[96:99]
	s_nop 2
	ds_read_b64_tr_b16 v[96:97], v153 offset:35040
	ds_read_b64_tr_b16 v[98:99], v153 offset:39392
	s_waitcnt lgkmcnt(4)
	v_mfma_f32_16x16x32_bf16 v[88:91], v[112:115], v[88:91], v[100:103]
	s_waitcnt lgkmcnt(2)
	v_mfma_f32_16x16x32_bf16 v[92:95], v[112:115], v[92:95], v[104:107]
	s_waitcnt lgkmcnt(0)
	v_mfma_f32_16x16x32_bf16 v[96:99], v[112:115], v[96:99], v[108:111]
	s_and_saveexec_b64 s[4:5], s[38:39]
	s_xor_b64 s[4:5], exec, s[4:5]
	s_or_saveexec_b64 s[4:5], s[4:5]
	v_add_f32_e32 v100, v2, v3
	v_mov_b64_e32 v[2:3], s[2:3]
	s_xor_b64 exec, exec, s[4:5]
	s_cbranch_execz .LBB0_333
	v_log_f32_e32 v2, v100
	s_lshl_b32 s60, s13, 2
	v_add_f32_e32 v0, v0, v2
	v_mov_b32_e32 v2, 0x6000
	v_mad_i64_i32 v[2:3], s[16:17], s16, v2, v[128:129]
	v_lshlrev_b64 v[2:3], 5, v[2:3]
	v_lshl_add_u64 v[2:3], s[82:83], 0, v[2:3]
	v_mul_f32_e32 v0, 0x3f317218, v0
	v_lshl_add_u64 v[2:3], v[2:3], 0, s[60:61]
	global_store_dword v[2:3], v0, off
	v_mov_b64_e32 v[2:3], s[2:3]
	s_branch .LBB0_333
